# attention: hazard-free s_nop between plain VALU max3/add chains removed (107 sites)
# speedup vs baseline: 1.0250x; 1.0250x over previous
.LBB0_691:
	s_add_i32 s4, s21, -3
	s_min_u32 s54, s4, s43
	s_mul_hi_u32 s4, s54, 0x55555556
	s_mul_i32 s4, s4, 3
	s_sub_i32 s4, s54, s4
	v_lshl_add_u32 v64, s4, 14, v153
	ds_read_b128 v[140:143], v64
	ds_read_b128 v[132:135], v64 offset:512
	ds_read_b128 v[136:139], v64 offset:2048
	ds_read_b128 v[120:123], v64 offset:2560
	ds_read_b128 v[128:131], v64 offset:4096
	ds_read_b128 v[116:119], v64 offset:4608
	ds_read_b128 v[124:127], v64 offset:6144
	ds_read_b128 v[112:115], v64 offset:6656
	s_nop 0
	v_max3_f32 v64, v48, v32, v49
	v_max3_f32 v65, v33, v50, v34
	v_max3_f32 v64, v64, v51, v35
	v_max3_f32 v65, v65, v52, v36
	v_max3_f32 v64, v64, v53, v37
	v_max3_f32 v65, v65, v54, v38
	v_max3_f32 v64, v64, v55, v39
	v_max3_f32 v65, v65, v56, v40
	v_max3_f32 v64, v64, v57, v41
	v_max3_f32 v65, v65, v58, v42
	v_max3_f32 v64, v64, v59, v43
	v_max3_f32 v65, v65, v60, v44
	v_max3_f32 v64, v64, v61, v45
	v_max3_f32 v65, v65, v62, v46
	v_max3_f32 v64, v64, v63, v47
	v_max_f32_e32 v65, v65, v65
	v_max_f32_e32 v64, v64, v64
	v_max_f32_e32 v64, v64, v65
	v_mov_b32_e32 v65, v64
	s_nop 1
	v_permlane32_swap_b32_e32 v64, v65
	v_max_f32_e32 v65, v65, v65
	v_max_f32_e32 v64, v64, v64
	v_max_f32_e32 v64, v64, v65
	v_cmp_lt_f32_e32 vcc, s97, v64
	v_cmp_lg_f32_e64 s[4:5], s96, v64
	s_nop 0
	v_cndmask_b32_e64 v65, 0, 1, vcc
	v_cndmask_b32_e64 v66, 0, 1, s[4:5]
	v_cndmask_b32_e64 v65, v66, v65, s[2:3]
	v_and_b32_e32 v65, 1, v65
	v_cmp_eq_u32_e64 s[6:7], 1, v65
	v_cmp_ne_u32_e32 vcc, 0, v65
	s_cbranch_vccz .LBB0_693
	v_cndmask_b32_e64 v64, 0, v64, s[6:7]
	v_exp_f32_e64 v66, -v64
	s_or_b64 s[4:5], s[2:3], s[4:5]
	s_andn2_b64 s[2:3], s[2:3], exec
	s_and_b64 s[4:5], s[4:5], exec
	v_pk_add_f32 v[48:49], v[48:49], v[64:65] op_sel_hi:[1,0] neg_lo:[0,1] neg_hi:[0,1]
	v_pk_add_f32 v[32:33], v[32:33], v[64:65] op_sel_hi:[1,0] neg_lo:[0,1] neg_hi:[0,1]
	v_pk_add_f32 v[50:51], v[50:51], v[64:65] op_sel_hi:[1,0] neg_lo:[0,1] neg_hi:[0,1]
	v_pk_add_f32 v[34:35], v[34:35], v[64:65] op_sel_hi:[1,0] neg_lo:[0,1] neg_hi:[0,1]
	v_pk_add_f32 v[52:53], v[52:53], v[64:65] op_sel_hi:[1,0] neg_lo:[0,1] neg_hi:[0,1]
	v_pk_add_f32 v[36:37], v[36:37], v[64:65] op_sel_hi:[1,0] neg_lo:[0,1] neg_hi:[0,1]
	v_pk_add_f32 v[54:55], v[54:55], v[64:65] op_sel_hi:[1,0] neg_lo:[0,1] neg_hi:[0,1]
	v_pk_add_f32 v[38:39], v[38:39], v[64:65] op_sel_hi:[1,0] neg_lo:[0,1] neg_hi:[0,1]
	v_pk_add_f32 v[56:57], v[56:57], v[64:65] op_sel_hi:[1,0] neg_lo:[0,1] neg_hi:[0,1]
	v_pk_add_f32 v[40:41], v[40:41], v[64:65] op_sel_hi:[1,0] neg_lo:[0,1] neg_hi:[0,1]
	v_pk_add_f32 v[58:59], v[58:59], v[64:65] op_sel_hi:[1,0] neg_lo:[0,1] neg_hi:[0,1]
	v_pk_add_f32 v[42:43], v[42:43], v[64:65] op_sel_hi:[1,0] neg_lo:[0,1] neg_hi:[0,1]
	v_pk_add_f32 v[60:61], v[60:61], v[64:65] op_sel_hi:[1,0] neg_lo:[0,1] neg_hi:[0,1]
	v_pk_add_f32 v[44:45], v[44:45], v[64:65] op_sel_hi:[1,0] neg_lo:[0,1] neg_hi:[0,1]
	v_pk_add_f32 v[62:63], v[62:63], v[64:65] op_sel_hi:[1,0] neg_lo:[0,1] neg_hi:[0,1]
	v_pk_add_f32 v[46:47], v[46:47], v[64:65] op_sel_hi:[1,0] neg_lo:[0,1] neg_hi:[0,1]
	v_add_f32_e32 v154, v154, v64
	v_mul_f32_e32 v150, v150, v66
	v_pk_mul_f32 v[30:31], v[30:31], v[66:67] op_sel_hi:[1,0]
	v_pk_mul_f32 v[28:29], v[28:29], v[66:67] op_sel_hi:[1,0]
	v_pk_mul_f32 v[26:27], v[26:27], v[66:67] op_sel_hi:[1,0]
	v_pk_mul_f32 v[24:25], v[24:25], v[66:67] op_sel_hi:[1,0]
	v_pk_mul_f32 v[22:23], v[22:23], v[66:67] op_sel_hi:[1,0]
	v_pk_mul_f32 v[20:21], v[20:21], v[66:67] op_sel_hi:[1,0]
	v_pk_mul_f32 v[18:19], v[18:19], v[66:67] op_sel_hi:[1,0]
	v_pk_mul_f32 v[16:17], v[16:17], v[66:67] op_sel_hi:[1,0]
	v_pk_mul_f32 v[14:15], v[14:15], v[66:67] op_sel_hi:[1,0]
	v_pk_mul_f32 v[12:13], v[12:13], v[66:67] op_sel_hi:[1,0]
	v_pk_mul_f32 v[10:11], v[10:11], v[66:67] op_sel_hi:[1,0]
	v_pk_mul_f32 v[8:9], v[8:9], v[66:67] op_sel_hi:[1,0]
	v_pk_mul_f32 v[6:7], v[6:7], v[66:67] op_sel_hi:[1,0]
	v_pk_mul_f32 v[4:5], v[4:5], v[66:67] op_sel_hi:[1,0]
	v_pk_mul_f32 v[2:3], v[2:3], v[66:67] op_sel_hi:[1,0]
	v_pk_mul_f32 v[0:1], v[0:1], v[66:67] op_sel_hi:[1,0]
	s_or_b64 s[2:3], s[2:3], s[4:5]
.LBB0_693:
	s_mul_hi_u32 s5, s48, 0xaaaaaaab
	s_lshr_b32 s5, s5, 1
	s_add_i32 s4, s21, -4
	s_mul_i32 s5, s5, 0xffff4000
	v_lshrrev_b64 v[64:65], s54, v[144:145]
	v_and_b32_e32 v64, 1, v64
	v_cmp_eq_u32_e32 vcc, 1, v64
	v_exp_f32_e32 v48, v48
	v_exp_f32_e32 v49, v49
	v_cndmask_b32_e64 v64, v249, -v154, vcc
	v_mov_b32_e32 v65, v64
	v_mov_b32_e32 v66, v64
	v_mov_b32_e32 v67, v64
	v_mov_b32_e32 v68, v64
	v_mov_b32_e32 v69, v64
	v_mov_b32_e32 v70, v64
	v_mov_b32_e32 v71, v64
	v_mov_b32_e32 v72, v64
	v_mov_b32_e32 v73, v64
	v_mov_b32_e32 v74, v64
	v_mov_b32_e32 v75, v64
	v_mov_b32_e32 v76, v64
	v_mov_b32_e32 v77, v64
	v_mov_b32_e32 v78, v64
	v_mov_b32_e32 v79, v64
	v_exp_f32_e32 v50, v50
	v_exp_f32_e32 v51, v51
	s_waitcnt lgkmcnt(0)
	v_mfma_f32_32x32x16_bf16 v[80:95], v[140:143], v[96:99], v[64:79]
	v_add_u32_e32 v140, s5, v155
	v_exp_f32_e32 v52, v52
	v_exp_f32_e32 v53, v53
	v_exp_f32_e32 v54, v54
	v_exp_f32_e32 v55, v55
	v_exp_f32_e32 v56, v56
	v_exp_f32_e32 v57, v57
	v_mfma_f32_32x32x16_bf16 v[64:79], v[132:135], v[96:99], v[64:79]
	v_exp_f32_e32 v58, v58
	v_exp_f32_e32 v59, v59
	v_exp_f32_e32 v60, v60
	v_exp_f32_e32 v61, v61
	v_exp_f32_e32 v62, v62
	v_exp_f32_e32 v63, v63
	v_mfma_f32_32x32x16_bf16 v[80:95], v[136:139], v[100:103], v[80:95]
	ds_read_b64_tr_b16 v[132:133], v140 offset:8192
	ds_read_b64_tr_b16 v[134:135], v140 offset:8704
	ds_read_b64_tr_b16 v[136:137], v140 offset:9216
	ds_read_b64_tr_b16 v[138:139], v140 offset:9728
	v_mfma_f32_32x32x16_bf16 v[80:95], v[128:131], v[104:107], v[80:95]
	v_mfma_f32_32x32x16_bf16 v[64:79], v[120:123], v[100:103], v[64:79]
	v_mfma_f32_32x32x16_bf16 v[80:95], v[124:127], v[108:111], v[80:95]
	ds_read_b64_tr_b16 v[120:121], v140 offset:12288
	ds_read_b64_tr_b16 v[122:123], v140 offset:12800
	ds_read_b64_tr_b16 v[124:125], v140 offset:13312
	ds_read_b64_tr_b16 v[126:127], v140 offset:13824
	s_nop 1
	s_nop 0
	v_add_f32_e32 v128, v215, v48
	v_add_f32_e32 v129, v215, v49
	v_cvt_pk_bf16_f32 v130, v60, v61
	v_add_f32_e32 v128, v128, v50
	v_mfma_f32_32x32x16_bf16 v[64:79], v[116:119], v[104:107], v[64:79]
	v_add_f32_e32 v116, v129, v51
	v_add_f32_e32 v117, v128, v52
	v_cvt_pk_bf16_f32 v118, v52, v53
	v_add_f32_e32 v116, v116, v53
	v_add_f32_e32 v117, v117, v54
	v_cvt_pk_bf16_f32 v119, v54, v55
	v_add_f32_e32 v116, v116, v55
	v_add_f32_e32 v117, v117, v56
	v_cvt_pk_bf16_f32 v128, v56, v57
	v_add_f32_e32 v116, v116, v57
	v_add_f32_e32 v117, v117, v58
	v_cvt_pk_bf16_f32 v129, v58, v59
	v_add_f32_e32 v116, v116, v59
	v_add_f32_e32 v117, v117, v60
	v_cvt_pk_bf16_f32 v131, v62, v63
	v_add_f32_e32 v116, v116, v61
	v_add_f32_e32 v141, v117, v62
	v_cvt_pk_bf16_f32 v117, v50, v51
	v_add_f32_e32 v142, v116, v63
	v_cvt_pk_bf16_f32 v116, v48, v49
	s_waitcnt lgkmcnt(0)
	s_nop 0
	v_mfma_f32_32x32x16_bf16 v[0:15], v[132:135], v[116:119], v[0:15]
	v_exp_f32_e32 v32, v32
	v_exp_f32_e32 v33, v33
	v_exp_f32_e32 v34, v34
	v_exp_f32_e32 v35, v35
	v_exp_f32_e32 v36, v36
	v_exp_f32_e32 v37, v37
	v_exp_f32_e32 v38, v38
	v_mfma_f32_32x32x16_bf16 v[16:31], v[120:123], v[116:119], v[16:31]
	v_exp_f32_e32 v39, v39
	v_exp_f32_e32 v40, v40
	v_exp_f32_e32 v41, v41
	v_exp_f32_e32 v42, v42
	v_exp_f32_e32 v43, v43
	v_exp_f32_e32 v44, v44
	v_exp_f32_e32 v45, v45
	v_mfma_f32_32x32x16_bf16 v[0:15], v[136:139], v[128:131], v[0:15]
	v_exp_f32_e32 v46, v46
	v_exp_f32_e32 v47, v47
	v_mfma_f32_32x32x16_bf16 v[16:31], v[124:127], v[128:131], v[16:31]
	ds_read_b64_tr_b16 v[116:117], v140 offset:10240
	ds_read_b64_tr_b16 v[118:119], v140 offset:10752
	ds_read_b64_tr_b16 v[120:121], v140 offset:14336
	ds_read_b64_tr_b16 v[122:123], v140 offset:14848
	ds_read_b64_tr_b16 v[124:125], v140 offset:11264
	ds_read_b64_tr_b16 v[126:127], v140 offset:11776
	ds_read_b64_tr_b16 v[128:129], v140 offset:15360
	ds_read_b64_tr_b16 v[130:131], v140 offset:15872
	s_nop 1
	s_nop 0
	v_add_f32_e32 v132, v141, v32
	v_add_f32_e32 v133, v142, v33
	v_cvt_pk_bf16_f32 v134, v36, v37
	v_add_f32_e32 v132, v132, v34
	v_add_f32_e32 v133, v133, v35
	v_cvt_pk_bf16_f32 v135, v38, v39
	v_add_f32_e32 v132, v132, v36
	v_add_f32_e32 v133, v133, v37
	v_cvt_pk_bf16_f32 v136, v40, v41
	v_add_f32_e32 v132, v132, v38
	v_add_f32_e32 v133, v133, v39
	v_cvt_pk_bf16_f32 v137, v42, v43
	v_add_f32_e32 v132, v132, v40
	v_add_f32_e32 v133, v133, v41
	v_cvt_pk_bf16_f32 v138, v44, v45
	v_add_f32_e32 v132, v132, v42
	v_add_f32_e32 v133, v133, v43
	v_cvt_pk_bf16_f32 v139, v46, v47
	v_add_f32_e32 v132, v132, v44
	v_add_f32_e32 v133, v133, v45
	v_add_f32_e32 v140, v132, v46
	v_add_f32_e32 v141, v133, v47
	v_cvt_pk_bf16_f32 v132, v32, v33
	s_nop 0
	v_cvt_pk_bf16_f32 v133, v34, v35
	v_add_f32_e32 v140, v140, v141
	s_waitcnt lgkmcnt(0)
	v_mfma_f32_32x32x16_bf16 v[0:15], v[116:119], v[132:135], v[0:15]
	s_waitcnt vmcnt(2) lgkmcnt(0)
	s_barrier
	v_add_f32_e32 v150, v150, v140
	s_cmp_ge_u32 s4, s43
	v_mfma_f32_32x32x16_bf16 v[16:31], v[120:123], v[132:135], v[16:31]
	v_mfma_f32_32x32x16_bf16 v[0:15], v[124:127], v[136:139], v[0:15]
	v_mfma_f32_32x32x16_bf16 v[16:31], v[128:131], v[136:139], v[16:31]
	v_mfma_f32_32x32x16_bf16 v[64:79], v[112:115], v[108:111], v[64:79]
	s_cbranch_scc1 .LBB0_688
	s_min_u32 s4, s21, s43
	s_mul_hi_u32 s5, s4, 0x55555556
	s_mul_i32 s5, s5, 3
	s_sub_i32 s5, s4, s5
	s_lshl_b32 s6, s5, 14
	s_mul_i32 s4, s4, 0x50000
	s_mov_b32 s5, s81
	v_lshl_add_u64 v[32:33], v[146:147], 0, s[4:5]
	s_mov_b64 s[4:5], 0xf40
	v_lshl_add_u64 v[32:33], v[32:33], 0, s[4:5]
	s_add_i32 m0, s61, s6
	s_add_i32 s4, s53, s95
	global_load_lds_dwordx4 v[32:33], off
	v_lshl_add_u64 v[32:33], v[148:149], 0, s[80:81]
	s_add_i32 m0, s4, 0x2000
	s_cmp_le_u32 s49, s39
	global_load_lds_dwordx4 v[32:33], off
	s_cbranch_scc1 .LBB0_696
	v_subrev_u32_e32 v32, 64, v156
	v_cmp_lt_i32_e32 vcc, -1, v32
	s_nop 1
	v_cndmask_b32_e32 v80, v249, v80, vcc
	v_cmp_lt_i32_e32 vcc, 31, v32
	s_nop 1
	v_cndmask_b32_e32 v64, v249, v64, vcc
	v_cmp_lt_i32_e32 vcc, 0, v32
	s_nop 1
	v_cndmask_b32_e32 v81, v249, v81, vcc
	v_cmp_lt_i32_e32 vcc, 32, v32
	s_nop 1
	v_cndmask_b32_e32 v65, v249, v65, vcc
	v_cmp_lt_i32_e32 vcc, 1, v32
	s_nop 1
	v_cndmask_b32_e32 v82, v249, v82, vcc
	v_cmp_lt_i32_e32 vcc, 33, v32
	s_nop 1
	v_cndmask_b32_e32 v66, v249, v66, vcc
	v_cmp_lt_i32_e32 vcc, 2, v32
	s_nop 1
	v_cndmask_b32_e32 v83, v249, v83, vcc
	v_cmp_lt_i32_e32 vcc, 34, v32
	s_nop 1
	v_cndmask_b32_e32 v67, v249, v67, vcc
	v_cmp_lt_i32_e32 vcc, 7, v32
	s_nop 1
	v_cndmask_b32_e32 v84, v249, v84, vcc
	v_cmp_lt_i32_e32 vcc, 39, v32
	s_nop 1
	v_cndmask_b32_e32 v68, v249, v68, vcc
	v_cmp_lt_i32_e32 vcc, 8, v32
	s_nop 1
	v_cndmask_b32_e32 v85, v249, v85, vcc
	v_cmp_lt_i32_e32 vcc, 40, v32
	s_nop 1
	v_cndmask_b32_e32 v69, v249, v69, vcc
	v_cmp_lt_i32_e32 vcc, 9, v32
	s_nop 1
	v_cndmask_b32_e32 v86, v249, v86, vcc
	v_cmp_lt_i32_e32 vcc, 41, v32
	s_nop 1
	v_cndmask_b32_e32 v70, v249, v70, vcc
	v_cmp_lt_i32_e32 vcc, 10, v32
	s_nop 1
	v_cndmask_b32_e32 v87, v249, v87, vcc
	v_cmp_lt_i32_e32 vcc, 42, v32
	s_nop 1
	v_cndmask_b32_e32 v71, v249, v71, vcc
	v_cmp_lt_i32_e32 vcc, 15, v32
	s_nop 1
	v_cndmask_b32_e32 v88, v249, v88, vcc
	v_cmp_lt_i32_e32 vcc, 47, v32
	s_nop 1
	v_cndmask_b32_e32 v72, v249, v72, vcc
	v_cmp_lt_i32_e32 vcc, 16, v32
	s_nop 1
	v_cndmask_b32_e32 v89, v249, v89, vcc
	v_cmp_lt_i32_e32 vcc, 48, v32
	s_nop 1
	v_cndmask_b32_e32 v73, v249, v73, vcc
	v_cmp_lt_i32_e32 vcc, 17, v32
	s_nop 1
	v_cndmask_b32_e32 v90, v249, v90, vcc
	v_cmp_lt_i32_e32 vcc, 49, v32
	s_nop 1
	v_cndmask_b32_e32 v74, v249, v74, vcc
	v_cmp_lt_i32_e32 vcc, 18, v32
	s_nop 1
	v_cndmask_b32_e32 v91, v249, v91, vcc
	v_cmp_lt_i32_e32 vcc, 50, v32
	s_nop 1
	v_cndmask_b32_e32 v75, v249, v75, vcc
	v_cmp_lt_i32_e32 vcc, 23, v32
	s_nop 1
	v_cndmask_b32_e32 v92, v249, v92, vcc
	v_cmp_lt_i32_e32 vcc, 55, v32
	s_nop 1
	v_cndmask_b32_e32 v76, v249, v76, vcc
	v_cmp_lt_i32_e32 vcc, 24, v32
	s_nop 1
	v_cndmask_b32_e32 v93, v249, v93, vcc
	v_cmp_lt_i32_e32 vcc, 56, v32
	s_nop 1
	v_cndmask_b32_e32 v77, v249, v77, vcc
	v_cmp_lt_i32_e32 vcc, 25, v32
	s_nop 1
	v_cndmask_b32_e32 v94, v249, v94, vcc
	v_cmp_lt_i32_e32 vcc, 57, v32
	s_nop 1
	v_cndmask_b32_e32 v78, v249, v78, vcc
	v_cmp_lt_i32_e32 vcc, 26, v32
	s_nop 1
	v_cndmask_b32_e32 v95, v249, v95, vcc
	v_cmp_lt_i32_e32 vcc, 58, v32
	s_nop 1
	v_cndmask_b32_e32 v79, v249, v79, vcc
.LBB0_696:
	v_add3_u32 v32, s52, v151, v152
	ds_read_b128 v[140:143], v32
	ds_read_b128 v[132:135], v32 offset:512
	ds_read_b128 v[136:139], v32 offset:2048
	ds_read_b128 v[120:123], v32 offset:2560
	ds_read_b128 v[128:131], v32 offset:4096
	ds_read_b128 v[116:119], v32 offset:4608
	ds_read_b128 v[124:127], v32 offset:6144
	ds_read_b128 v[112:115], v32 offset:6656
	s_nop 0
	v_max3_f32 v32, v80, v64, v81
	v_max3_f32 v33, v65, v82, v66
	v_max3_f32 v32, v32, v83, v67
	v_max3_f32 v33, v33, v84, v68
	v_max3_f32 v32, v32, v85, v69
	v_max3_f32 v33, v33, v86, v70
	v_max3_f32 v32, v32, v87, v71
	v_max3_f32 v33, v33, v88, v72
	v_max3_f32 v32, v32, v89, v73
	v_max3_f32 v33, v33, v90, v74
	v_max3_f32 v32, v32, v91, v75
	v_max3_f32 v33, v33, v92, v76
	v_max3_f32 v32, v32, v93, v77
	v_max3_f32 v33, v33, v94, v78
	v_max3_f32 v32, v32, v95, v79
	v_max_f32_e32 v33, v33, v33
	v_max_f32_e32 v32, v32, v32
	v_max_f32_e32 v32, v32, v33
	v_mov_b32_e32 v33, v32
	s_nop 1
	v_permlane32_swap_b32_e32 v32, v33
	v_max_f32_e32 v33, v33, v33
	v_max_f32_e32 v32, v32, v32
	v_max_f32_e32 v32, v32, v33
	v_cmp_lt_f32_e32 vcc, s97, v32
	v_cmp_lg_f32_e64 s[4:5], s96, v32
	s_nop 0
	v_cndmask_b32_e64 v33, 0, 1, vcc
	v_cndmask_b32_e64 v34, 0, 1, s[4:5]
	v_cndmask_b32_e64 v33, v34, v33, s[2:3]
	v_and_b32_e32 v33, 1, v33
	v_cmp_eq_u32_e64 s[6:7], 1, v33
	v_cmp_ne_u32_e32 vcc, 0, v33
	s_cbranch_vccnz .LBB0_686
	v_xor_b32_e32 v32, 0x80000000, v154
	s_branch .LBB0_687

.LBB0_704:
	s_add_i32 s4, s18, -3
	s_min_i32 s4, s4, s43
	s_mul_hi_u32 s5, s4, 0xaaaaaaab
	s_lshr_b32 s5, s5, 1
	s_mul_i32 s5, s5, 3
	s_sub_i32 s4, s4, s5
	v_lshl_add_u32 v84, s4, 14, v168
	ds_read_b128 v[80:83], v84
	ds_read_b128 v[152:155], v84 offset:512
	ds_read_b128 v[148:151], v84 offset:2048
	ds_read_b128 v[136:139], v84 offset:2560
	ds_read_b128 v[144:147], v84 offset:4096
	ds_read_b128 v[132:135], v84 offset:4608
	ds_read_b128 v[140:143], v84 offset:6144
	ds_read_b128 v[128:131], v84 offset:6656
	s_nop 0
	v_max3_f32 v84, v48, v64, v49
	v_max3_f32 v85, v65, v50, v66
	v_max3_f32 v84, v84, v51, v67
	v_max3_f32 v85, v85, v52, v68
	v_max3_f32 v84, v84, v53, v69
	v_max3_f32 v85, v85, v54, v70
	v_max3_f32 v84, v84, v55, v71
	v_max3_f32 v85, v85, v56, v72
	v_max3_f32 v84, v84, v57, v73
	v_max3_f32 v85, v85, v58, v74
	v_max3_f32 v84, v84, v59, v75
	v_max3_f32 v85, v85, v60, v76
	v_max3_f32 v84, v84, v61, v77
	v_max3_f32 v85, v85, v62, v78
	v_max3_f32 v84, v84, v63, v79
	v_max_f32_e32 v85, v85, v85
	v_max_f32_e32 v84, v84, v84
	v_max_f32_e32 v84, v84, v85
	v_mov_b32_e32 v85, v84
	s_nop 1
	v_permlane32_swap_b32_e32 v84, v85
	v_max_f32_e32 v85, v85, v85
	v_max_f32_e32 v84, v84, v84
	v_max_f32_e32 v84, v84, v85
	v_cmp_lt_f32_e32 vcc, s97, v84
	v_cmp_lg_f32_e64 s[4:5], s96, v84
	s_nop 0
	v_cndmask_b32_e64 v85, 0, 1, vcc
	v_cndmask_b32_e64 v86, 0, 1, s[4:5]
	v_cndmask_b32_e64 v85, v86, v85, s[2:3]
	v_and_b32_e32 v85, 1, v85
	v_cmp_eq_u32_e64 s[6:7], 1, v85
	v_cmp_ne_u32_e32 vcc, 0, v85
	s_cbranch_vccz .LBB0_706
	v_cndmask_b32_e64 v32, 0, v84, s[6:7]
	v_exp_f32_e64 v34, -v32
	s_or_b64 s[4:5], s[2:3], s[4:5]
	v_add_f32_e32 v171, v171, v32
	v_pk_add_f32 v[48:49], v[48:49], v[32:33] op_sel_hi:[1,0] neg_lo:[0,1] neg_hi:[0,1]
	v_pk_add_f32 v[64:65], v[64:65], v[32:33] op_sel_hi:[1,0] neg_lo:[0,1] neg_hi:[0,1]
	v_pk_add_f32 v[50:51], v[50:51], v[32:33] op_sel_hi:[1,0] neg_lo:[0,1] neg_hi:[0,1]
	v_pk_add_f32 v[66:67], v[66:67], v[32:33] op_sel_hi:[1,0] neg_lo:[0,1] neg_hi:[0,1]
	v_pk_add_f32 v[52:53], v[52:53], v[32:33] op_sel_hi:[1,0] neg_lo:[0,1] neg_hi:[0,1]
	v_pk_add_f32 v[68:69], v[68:69], v[32:33] op_sel_hi:[1,0] neg_lo:[0,1] neg_hi:[0,1]
	v_pk_add_f32 v[54:55], v[54:55], v[32:33] op_sel_hi:[1,0] neg_lo:[0,1] neg_hi:[0,1]
	v_pk_add_f32 v[70:71], v[70:71], v[32:33] op_sel_hi:[1,0] neg_lo:[0,1] neg_hi:[0,1]
	v_pk_add_f32 v[56:57], v[56:57], v[32:33] op_sel_hi:[1,0] neg_lo:[0,1] neg_hi:[0,1]
	v_pk_add_f32 v[72:73], v[72:73], v[32:33] op_sel_hi:[1,0] neg_lo:[0,1] neg_hi:[0,1]
	v_pk_add_f32 v[58:59], v[58:59], v[32:33] op_sel_hi:[1,0] neg_lo:[0,1] neg_hi:[0,1]
	v_pk_add_f32 v[74:75], v[74:75], v[32:33] op_sel_hi:[1,0] neg_lo:[0,1] neg_hi:[0,1]
	v_pk_add_f32 v[60:61], v[60:61], v[32:33] op_sel_hi:[1,0] neg_lo:[0,1] neg_hi:[0,1]
	v_pk_add_f32 v[76:77], v[76:77], v[32:33] op_sel_hi:[1,0] neg_lo:[0,1] neg_hi:[0,1]
	v_pk_add_f32 v[62:63], v[62:63], v[32:33] op_sel_hi:[1,0] neg_lo:[0,1] neg_hi:[0,1]
	v_pk_add_f32 v[78:79], v[78:79], v[32:33] op_sel_hi:[1,0] neg_lo:[0,1] neg_hi:[0,1]
	v_xor_b32_e32 v32, 0x80000000, v171
	s_andn2_b64 s[2:3], s[2:3], exec
	s_and_b64 s[4:5], s[4:5], exec
	v_mul_f32_e32 v165, v165, v34
	v_pk_mul_f32 v[14:15], v[14:15], v[34:35] op_sel_hi:[1,0]
	v_pk_mul_f32 v[12:13], v[12:13], v[34:35] op_sel_hi:[1,0]
	v_pk_mul_f32 v[10:11], v[10:11], v[34:35] op_sel_hi:[1,0]
	v_pk_mul_f32 v[8:9], v[8:9], v[34:35] op_sel_hi:[1,0]
	v_pk_mul_f32 v[6:7], v[6:7], v[34:35] op_sel_hi:[1,0]
	v_pk_mul_f32 v[4:5], v[4:5], v[34:35] op_sel_hi:[1,0]
	v_pk_mul_f32 v[2:3], v[2:3], v[34:35] op_sel_hi:[1,0]
	v_pk_mul_f32 v[0:1], v[0:1], v[34:35] op_sel_hi:[1,0]
	v_pk_mul_f32 v[30:31], v[30:31], v[34:35] op_sel_hi:[1,0]
	v_pk_mul_f32 v[28:29], v[28:29], v[34:35] op_sel_hi:[1,0]
	v_pk_mul_f32 v[26:27], v[26:27], v[34:35] op_sel_hi:[1,0]
	v_pk_mul_f32 v[24:25], v[24:25], v[34:35] op_sel_hi:[1,0]
	v_pk_mul_f32 v[22:23], v[22:23], v[34:35] op_sel_hi:[1,0]
	v_pk_mul_f32 v[20:21], v[20:21], v[34:35] op_sel_hi:[1,0]
	v_pk_mul_f32 v[18:19], v[18:19], v[34:35] op_sel_hi:[1,0]
	v_pk_mul_f32 v[16:17], v[16:17], v[34:35] op_sel_hi:[1,0]
	v_mov_b32_e32 v33, v32
	v_mov_b32_e32 v34, v32
	v_mov_b32_e32 v35, v32
	v_mov_b32_e32 v36, v32
	v_mov_b32_e32 v37, v32
	v_mov_b32_e32 v38, v32
	v_mov_b32_e32 v39, v32
	v_mov_b32_e32 v40, v32
	v_mov_b32_e32 v41, v32
	v_mov_b32_e32 v42, v32
	v_mov_b32_e32 v43, v32
	v_mov_b32_e32 v44, v32
	v_mov_b32_e32 v45, v32
	v_mov_b32_e32 v46, v32
	v_mov_b32_e32 v47, v32
	s_or_b64 s[2:3], s[2:3], s[4:5]
.LBB0_706:
	s_mul_hi_u32 s5, s16, 0xaaaaaaab
	s_lshr_b32 s5, s5, 1
	s_add_i32 s4, s18, -4
	s_mul_i32 s5, s5, 0xffff4000
	s_waitcnt lgkmcnt(0)
	v_mfma_f32_32x32x16_bf16 v[96:111], v[80:83], v[112:115], v[32:47]
	v_add_u32_e32 v184, s5, v169
	ds_read_b64_tr_b16 v[172:173], v184 offset:8192
	ds_read_b64_tr_b16 v[174:175], v184 offset:8704
	ds_read_b64_tr_b16 v[176:177], v184 offset:9216
	ds_read_b64_tr_b16 v[178:179], v184 offset:9728
	v_exp_f32_e32 v48, v48
	v_exp_f32_e32 v49, v49
	v_exp_f32_e32 v50, v50
	v_exp_f32_e32 v51, v51
	v_exp_f32_e32 v52, v52
	v_mfma_f32_32x32x16_bf16 v[80:95], v[152:155], v[112:115], v[32:47]
	v_exp_f32_e32 v53, v53
	v_exp_f32_e32 v54, v54
	v_exp_f32_e32 v55, v55
	v_exp_f32_e32 v56, v56
	v_exp_f32_e32 v57, v57
	v_exp_f32_e32 v58, v58
	v_exp_f32_e32 v59, v59
	v_mfma_f32_32x32x16_bf16 v[96:111], v[148:151], v[116:119], v[96:111]
	v_exp_f32_e32 v60, v60
	v_exp_f32_e32 v61, v61
	v_exp_f32_e32 v62, v62
	v_exp_f32_e32 v63, v63
	ds_read_b64_tr_b16 v[148:149], v184 offset:12288
	ds_read_b64_tr_b16 v[150:151], v184 offset:12800
	ds_read_b64_tr_b16 v[152:153], v184 offset:13312
	ds_read_b64_tr_b16 v[154:155], v184 offset:13824
	s_nop 1
	v_mfma_f32_32x32x16_bf16 v[96:111], v[144:147], v[120:123], v[96:111]
	v_add_f32_e32 v144, v215, v49
	v_add_f32_e32 v185, v215, v48
	v_add_f32_e32 v145, v185, v50
	v_add_f32_e32 v144, v144, v51
	s_nop 0
	v_add_f32_e32 v145, v145, v52
	v_mfma_f32_32x32x16_bf16 v[80:95], v[136:139], v[116:119], v[80:95]
	v_add_f32_e32 v144, v144, v53
	v_add_f32_e32 v145, v145, v54
	v_cvt_pk_bf16_f32 v136, v48, v49
	v_add_f32_e32 v144, v144, v55
	v_cvt_pk_bf16_f32 v137, v50, v51
	v_cvt_pk_bf16_f32 v138, v52, v53
	v_cvt_pk_bf16_f32 v139, v54, v55
	v_mfma_f32_32x32x16_bf16 v[96:111], v[140:143], v[124:127], v[96:111]
	v_add_f32_e32 v140, v145, v56
	v_add_f32_e32 v141, v144, v57
	v_cvt_pk_bf16_f32 v142, v60, v61
	v_add_f32_e32 v140, v140, v58
	v_add_f32_e32 v141, v141, v59
	v_cvt_pk_bf16_f32 v143, v62, v63
	v_add_f32_e32 v140, v140, v60
	v_mfma_f32_32x32x16_bf16 v[80:95], v[132:135], v[120:123], v[80:95]
	v_add_f32_e32 v141, v141, v61
	v_add_f32_e32 v185, v140, v62
	v_cvt_pk_bf16_f32 v140, v56, v57
	v_add_f32_e32 v186, v141, v63
	v_cvt_pk_bf16_f32 v141, v58, v59
	s_waitcnt lgkmcnt(0)
	v_mfma_f32_32x32x16_bf16 v[16:31], v[172:175], v[136:139], v[16:31]
	v_exp_f32_e32 v64, v64
	v_exp_f32_e32 v65, v65
	v_exp_f32_e32 v66, v66
	v_exp_f32_e32 v67, v67
	v_exp_f32_e32 v68, v68
	v_exp_f32_e32 v69, v69
	v_exp_f32_e32 v70, v70
	v_mfma_f32_32x32x16_bf16 v[0:15], v[148:151], v[136:139], v[0:15]
	v_exp_f32_e32 v71, v71
	v_exp_f32_e32 v72, v72
	v_exp_f32_e32 v73, v73
	v_exp_f32_e32 v74, v74
	v_exp_f32_e32 v75, v75
	v_exp_f32_e32 v76, v76
	v_exp_f32_e32 v77, v77
	v_mfma_f32_32x32x16_bf16 v[16:31], v[176:179], v[140:143], v[16:31]
	v_exp_f32_e32 v78, v78
	v_exp_f32_e32 v79, v79
	v_mfma_f32_32x32x16_bf16 v[0:15], v[152:155], v[140:143], v[0:15]
	ds_read_b64_tr_b16 v[132:133], v184 offset:10240
	ds_read_b64_tr_b16 v[134:135], v184 offset:10752
	ds_read_b64_tr_b16 v[136:137], v184 offset:14336
	ds_read_b64_tr_b16 v[138:139], v184 offset:14848
	ds_read_b64_tr_b16 v[140:141], v184 offset:11264
	ds_read_b64_tr_b16 v[142:143], v184 offset:11776
	ds_read_b64_tr_b16 v[144:145], v184 offset:15360
	ds_read_b64_tr_b16 v[146:147], v184 offset:15872
	s_nop 1
	s_nop 0
	v_add_f32_e32 v148, v185, v64
	v_add_f32_e32 v149, v186, v65
	v_cvt_pk_bf16_f32 v150, v68, v69
	v_add_f32_e32 v148, v148, v66
	v_add_f32_e32 v149, v149, v67
	v_cvt_pk_bf16_f32 v151, v70, v71
	v_add_f32_e32 v148, v148, v68
	v_add_f32_e32 v149, v149, v69
	v_cvt_pk_bf16_f32 v152, v72, v73
	v_add_f32_e32 v148, v148, v70
	v_add_f32_e32 v149, v149, v71
	v_cvt_pk_bf16_f32 v153, v74, v75
	v_add_f32_e32 v148, v148, v72
	v_add_f32_e32 v149, v149, v73
	v_cvt_pk_bf16_f32 v154, v76, v77
	v_add_f32_e32 v148, v148, v74
	v_add_f32_e32 v149, v149, v75
	v_cvt_pk_bf16_f32 v155, v78, v79
	v_add_f32_e32 v148, v148, v76
	v_add_f32_e32 v149, v149, v77
	v_add_f32_e32 v172, v148, v78
	v_add_f32_e32 v173, v149, v79
	v_cvt_pk_bf16_f32 v148, v64, v65
	s_nop 0
	v_cvt_pk_bf16_f32 v149, v66, v67
	v_add_f32_e32 v172, v172, v173
	s_waitcnt lgkmcnt(0)
	v_mfma_f32_32x32x16_bf16 v[16:31], v[132:135], v[148:151], v[16:31]
	s_waitcnt vmcnt(2) lgkmcnt(0)
	s_barrier
	v_add_f32_e32 v165, v165, v172
	s_cmp_ge_u32 s4, s43
	v_mfma_f32_32x32x16_bf16 v[0:15], v[136:139], v[148:151], v[0:15]
	v_mfma_f32_32x32x16_bf16 v[16:31], v[140:143], v[152:155], v[16:31]
	v_mfma_f32_32x32x16_bf16 v[0:15], v[144:147], v[152:155], v[0:15]
	v_mfma_f32_32x32x16_bf16 v[80:95], v[128:131], v[124:127], v[80:95]
	s_cbranch_scc1 .LBB0_701
	s_min_i32 s4, s18, s43
	s_mul_hi_u32 s5, s4, 0xaaaaaaab
	s_lshr_b32 s5, s5, 1
	s_mul_i32 s5, s5, 3
	s_sub_i32 s5, s4, s5
	s_lshl_b32 s6, s5, 14
	s_mul_i32 s4, s4, 0x50000
	s_mov_b32 s5, s81
	v_lshl_add_u64 v[48:49], v[160:161], 0, s[4:5]
	s_add_i32 m0, s61, s6
	s_add_i32 s4, s23, s95
	global_load_lds_dwordx4 v[48:49], off
	v_lshl_add_u64 v[48:49], v[162:163], 0, s[80:81]
	s_add_i32 m0, s4, 0x2000
	s_add_i32 s6, s20, 64
	global_load_lds_dwordx4 v[48:49], off
	s_add_i32 s4, s20, 0x7f
	s_cmp_gt_u32 s4, s39
	s_cselect_b64 s[4:5], -1, 0
	s_cmp_lt_i32 s6, s17
	s_cselect_b64 s[6:7], -1, 0
	s_or_b64 s[4:5], s[4:5], s[6:7]
	s_andn2_b64 vcc, exec, s[4:5]
	s_cbranch_vccnz .LBB0_709
	v_add_u32_e32 v48, 59, v170
	v_add_u32_e32 v49, 27, v170
	v_cmp_gt_u32_e32 vcc, s94, v48
	v_add_u32_e32 v48, 58, v170
	s_nop 0
	v_cndmask_b32_e32 v96, v249, v96, vcc
	v_cmp_gt_u32_e32 vcc, s94, v49
	v_add_u32_e32 v49, 26, v170
	s_nop 0
	v_cndmask_b32_e32 v80, v249, v80, vcc
	v_cmp_gt_u32_e32 vcc, s94, v48
	v_add_u32_e32 v48, 57, v170
	s_nop 0
	v_cndmask_b32_e32 v97, v249, v97, vcc
	v_cmp_gt_u32_e32 vcc, s94, v49
	v_add_u32_e32 v49, 25, v170
	s_nop 0
	v_cndmask_b32_e32 v81, v249, v81, vcc
	v_cmp_gt_u32_e32 vcc, s94, v48
	v_add_u32_e32 v48, 56, v170
	s_nop 0
	v_cndmask_b32_e32 v98, v249, v98, vcc
	v_cmp_gt_u32_e32 vcc, s94, v49
	v_add_u32_e32 v49, 24, v170
	s_nop 0
	v_cndmask_b32_e32 v82, v249, v82, vcc
	v_cmp_gt_u32_e32 vcc, s94, v48
	v_add_u32_e32 v48, 51, v170
	s_nop 0
	v_cndmask_b32_e32 v99, v249, v99, vcc
	v_cmp_gt_u32_e32 vcc, s94, v49
	v_add_u32_e32 v49, 19, v170
	s_nop 0
	v_cndmask_b32_e32 v83, v249, v83, vcc
	v_cmp_gt_u32_e32 vcc, s94, v48
	v_add_u32_e32 v48, 50, v170
	s_nop 0
	v_cndmask_b32_e32 v100, v249, v100, vcc
	v_cmp_gt_u32_e32 vcc, s94, v49
	v_add_u32_e32 v49, 18, v170
	s_nop 0
	v_cndmask_b32_e32 v84, v249, v84, vcc
	v_cmp_gt_u32_e32 vcc, s94, v48
	v_add_u32_e32 v48, 49, v170
	s_nop 0
	v_cndmask_b32_e32 v101, v249, v101, vcc
	v_cmp_gt_u32_e32 vcc, s94, v49
	v_add_u32_e32 v49, 17, v170
	s_nop 0
	v_cndmask_b32_e32 v85, v249, v85, vcc
	v_cmp_gt_u32_e32 vcc, s94, v48
	v_add_u32_e32 v48, 48, v170
	s_nop 0
	v_cndmask_b32_e32 v102, v249, v102, vcc
	v_cmp_gt_u32_e32 vcc, s94, v49
	v_add_u32_e32 v49, 16, v170
	s_nop 0
	v_cndmask_b32_e32 v86, v249, v86, vcc
	v_cmp_gt_u32_e32 vcc, s94, v48
	v_add_u32_e32 v48, 43, v170
	s_nop 0
	v_cndmask_b32_e32 v103, v249, v103, vcc
	v_cmp_gt_u32_e32 vcc, s94, v49
	v_add_u32_e32 v49, 11, v170
	s_nop 0
	v_cndmask_b32_e32 v87, v249, v87, vcc
	v_cmp_gt_u32_e32 vcc, s94, v48
	v_add_u32_e32 v48, 42, v170
	s_nop 0
	v_cndmask_b32_e32 v104, v249, v104, vcc
	v_cmp_gt_u32_e32 vcc, s94, v49
	v_add_u32_e32 v49, 10, v170
	s_nop 0
	v_cndmask_b32_e32 v88, v249, v88, vcc
	v_cmp_gt_u32_e32 vcc, s94, v48
	v_add_u32_e32 v48, 41, v170
	s_nop 0
	v_cndmask_b32_e32 v105, v249, v105, vcc
	v_cmp_gt_u32_e32 vcc, s94, v49
	v_add_u32_e32 v49, 9, v170
	s_nop 0
	v_cndmask_b32_e32 v89, v249, v89, vcc
	v_cmp_gt_u32_e32 vcc, s94, v48
	v_add_u32_e32 v48, 40, v170
	s_nop 0
	v_cndmask_b32_e32 v106, v249, v106, vcc
	v_cmp_gt_u32_e32 vcc, s94, v49
	v_add_u32_e32 v49, 8, v170
	s_nop 0
	v_cndmask_b32_e32 v90, v249, v90, vcc
	v_cmp_gt_u32_e32 vcc, s94, v48
	v_add_u32_e32 v48, 35, v170
	s_nop 0
	v_cndmask_b32_e32 v107, v249, v107, vcc
	v_cmp_gt_u32_e32 vcc, s94, v49
	v_add_u32_e32 v49, 3, v170
	s_nop 0
	v_cndmask_b32_e32 v91, v249, v91, vcc
	v_cmp_gt_u32_e32 vcc, s94, v48
	v_add_u32_e32 v48, 34, v170
	s_nop 0
	v_cndmask_b32_e32 v108, v249, v108, vcc
	v_cmp_gt_u32_e32 vcc, s94, v49
	v_add_u32_e32 v49, 2, v170
	s_nop 0
	v_cndmask_b32_e32 v92, v249, v92, vcc
	v_cmp_gt_u32_e32 vcc, s94, v48
	v_add_u32_e32 v48, 33, v170
	s_nop 0
	v_cndmask_b32_e32 v109, v249, v109, vcc
	v_cmp_gt_u32_e32 vcc, s94, v49
	v_add_u32_e32 v49, 1, v170
	s_nop 0
	v_cndmask_b32_e32 v93, v249, v93, vcc
	v_cmp_gt_u32_e32 vcc, s94, v48
	v_add_u32_e32 v48, 32, v170
	s_nop 0
	v_cndmask_b32_e32 v110, v249, v110, vcc
	v_cmp_gt_u32_e32 vcc, s94, v49
	s_nop 1
	v_cndmask_b32_e32 v94, v249, v94, vcc
	v_cmp_gt_u32_e32 vcc, s94, v48
	s_nop 1
	v_cndmask_b32_e32 v111, v249, v111, vcc
	v_cmp_gt_u32_e32 vcc, s94, v170
	s_nop 1
	v_cndmask_b32_e32 v95, v249, v95, vcc
.LBB0_709:
	v_add3_u32 v48, s22, v166, v167
	ds_read_b128 v[64:67], v48
	ds_read_b128 v[152:155], v48 offset:512
	ds_read_b128 v[140:143], v48 offset:2048
	ds_read_b128 v[132:135], v48 offset:2560
	ds_read_b128 v[144:147], v48 offset:4096
	ds_read_b128 v[136:139], v48 offset:4608
	ds_read_b128 v[148:151], v48 offset:6144
	ds_read_b128 v[128:131], v48 offset:6656
	s_nop 0
	v_max3_f32 v48, v96, v80, v97
	v_max3_f32 v49, v81, v98, v82
	v_max3_f32 v48, v48, v99, v83
	v_max3_f32 v49, v49, v100, v84
	v_max3_f32 v48, v48, v101, v85
	v_max3_f32 v49, v49, v102, v86
	v_max3_f32 v48, v48, v103, v87
	v_max3_f32 v49, v49, v104, v88
	v_max3_f32 v48, v48, v105, v89
	v_max3_f32 v49, v49, v106, v90
	v_max3_f32 v48, v48, v107, v91
	v_max3_f32 v49, v49, v108, v92
	v_max3_f32 v48, v48, v109, v93
	v_max3_f32 v49, v49, v110, v94
	v_max3_f32 v48, v48, v111, v95
	v_max_f32_e32 v49, v49, v49
	v_max_f32_e32 v48, v48, v48
	v_max_f32_e32 v48, v48, v49
	v_mov_b32_e32 v49, v48
	s_nop 1
	v_permlane32_swap_b32_e32 v48, v49
	v_max_f32_e32 v49, v49, v49
	v_max_f32_e32 v48, v48, v48
	v_max_f32_e32 v48, v48, v49
	v_cmp_lt_f32_e32 vcc, s97, v48
	v_cmp_lg_f32_e64 s[4:5], s96, v48
	s_nop 0
	v_cndmask_b32_e64 v49, 0, 1, vcc
	v_cndmask_b32_e64 v50, 0, 1, s[4:5]
	v_cndmask_b32_e64 v49, v50, v49, s[2:3]
	v_and_b32_e32 v49, 1, v49
	v_cmp_eq_u32_e64 s[6:7], 1, v49
	v_cmp_ne_u32_e32 vcc, 0, v49
	s_cbranch_vccz .LBB0_700
	v_cndmask_b32_e64 v32, 0, v48, s[6:7]
	v_exp_f32_e64 v34, -v32
	s_or_b64 s[4:5], s[2:3], s[4:5]
	v_add_f32_e32 v171, v171, v32
	v_pk_add_f32 v[96:97], v[96:97], v[32:33] op_sel_hi:[1,0] neg_lo:[0,1] neg_hi:[0,1]
	v_pk_add_f32 v[80:81], v[80:81], v[32:33] op_sel_hi:[1,0] neg_lo:[0,1] neg_hi:[0,1]
	v_pk_add_f32 v[98:99], v[98:99], v[32:33] op_sel_hi:[1,0] neg_lo:[0,1] neg_hi:[0,1]
	v_pk_add_f32 v[82:83], v[82:83], v[32:33] op_sel_hi:[1,0] neg_lo:[0,1] neg_hi:[0,1]
	v_pk_add_f32 v[100:101], v[100:101], v[32:33] op_sel_hi:[1,0] neg_lo:[0,1] neg_hi:[0,1]
	v_pk_add_f32 v[84:85], v[84:85], v[32:33] op_sel_hi:[1,0] neg_lo:[0,1] neg_hi:[0,1]
	v_pk_add_f32 v[102:103], v[102:103], v[32:33] op_sel_hi:[1,0] neg_lo:[0,1] neg_hi:[0,1]
	v_pk_add_f32 v[86:87], v[86:87], v[32:33] op_sel_hi:[1,0] neg_lo:[0,1] neg_hi:[0,1]
	v_pk_add_f32 v[104:105], v[104:105], v[32:33] op_sel_hi:[1,0] neg_lo:[0,1] neg_hi:[0,1]
	v_pk_add_f32 v[88:89], v[88:89], v[32:33] op_sel_hi:[1,0] neg_lo:[0,1] neg_hi:[0,1]
	v_pk_add_f32 v[106:107], v[106:107], v[32:33] op_sel_hi:[1,0] neg_lo:[0,1] neg_hi:[0,1]
	v_pk_add_f32 v[90:91], v[90:91], v[32:33] op_sel_hi:[1,0] neg_lo:[0,1] neg_hi:[0,1]
	v_pk_add_f32 v[108:109], v[108:109], v[32:33] op_sel_hi:[1,0] neg_lo:[0,1] neg_hi:[0,1]
	v_pk_add_f32 v[92:93], v[92:93], v[32:33] op_sel_hi:[1,0] neg_lo:[0,1] neg_hi:[0,1]
	v_pk_add_f32 v[110:111], v[110:111], v[32:33] op_sel_hi:[1,0] neg_lo:[0,1] neg_hi:[0,1]
	v_pk_add_f32 v[94:95], v[94:95], v[32:33] op_sel_hi:[1,0] neg_lo:[0,1] neg_hi:[0,1]
	v_xor_b32_e32 v32, 0x80000000, v171
	s_andn2_b64 s[2:3], s[2:3], exec
	s_and_b64 s[4:5], s[4:5], exec
	v_mul_f32_e32 v165, v165, v34
	v_pk_mul_f32 v[14:15], v[14:15], v[34:35] op_sel_hi:[1,0]
	v_pk_mul_f32 v[12:13], v[12:13], v[34:35] op_sel_hi:[1,0]
	v_pk_mul_f32 v[10:11], v[10:11], v[34:35] op_sel_hi:[1,0]
	v_pk_mul_f32 v[8:9], v[8:9], v[34:35] op_sel_hi:[1,0]
	v_pk_mul_f32 v[6:7], v[6:7], v[34:35] op_sel_hi:[1,0]
	v_pk_mul_f32 v[4:5], v[4:5], v[34:35] op_sel_hi:[1,0]
	v_pk_mul_f32 v[2:3], v[2:3], v[34:35] op_sel_hi:[1,0]
	v_pk_mul_f32 v[0:1], v[0:1], v[34:35] op_sel_hi:[1,0]
	v_pk_mul_f32 v[30:31], v[30:31], v[34:35] op_sel_hi:[1,0]
	v_pk_mul_f32 v[28:29], v[28:29], v[34:35] op_sel_hi:[1,0]
	v_pk_mul_f32 v[26:27], v[26:27], v[34:35] op_sel_hi:[1,0]
	v_pk_mul_f32 v[24:25], v[24:25], v[34:35] op_sel_hi:[1,0]
	v_pk_mul_f32 v[22:23], v[22:23], v[34:35] op_sel_hi:[1,0]
	v_pk_mul_f32 v[20:21], v[20:21], v[34:35] op_sel_hi:[1,0]
	v_pk_mul_f32 v[18:19], v[18:19], v[34:35] op_sel_hi:[1,0]
	v_pk_mul_f32 v[16:17], v[16:17], v[34:35] op_sel_hi:[1,0]
	v_mov_b32_e32 v33, v32
	v_mov_b32_e32 v34, v32
	v_mov_b32_e32 v35, v32
	v_mov_b32_e32 v36, v32
	v_mov_b32_e32 v37, v32
	v_mov_b32_e32 v38, v32
	v_mov_b32_e32 v39, v32
	v_mov_b32_e32 v40, v32
	v_mov_b32_e32 v41, v32
	v_mov_b32_e32 v42, v32
	v_mov_b32_e32 v43, v32
	v_mov_b32_e32 v44, v32
	v_mov_b32_e32 v45, v32
	v_mov_b32_e32 v46, v32
	v_mov_b32_e32 v47, v32
	s_or_b64 s[2:3], s[2:3], s[4:5]
	s_branch .LBB0_700

.LBB0_719:
	s_add_i32 s4, s19, -3
	s_min_u32 s4, s4, s22
	s_mul_hi_u32 s5, s4, 0x55555556
	s_mul_i32 s5, s5, 3
	s_sub_i32 s4, s4, s5
	s_mulk_i32 s4, 0x5000
	v_add_u32_e32 v84, s4, v194
	ds_read_b128 v[80:83], v84
	ds_read_b128 v[176:179], v84 offset:512
	ds_read_b128 v[168:171], v84 offset:2048
	ds_read_b128 v[152:155], v84 offset:2560
	ds_read_b128 v[172:175], v84 offset:4096
	ds_read_b128 v[148:151], v84 offset:4608
	ds_read_b128 v[164:167], v84 offset:6144
	ds_read_b128 v[144:147], v84 offset:6656
	ds_read_b128 v[160:163], v84 offset:8192
	ds_read_b128 v[140:143], v84 offset:8704
	ds_read_b128 v[156:159], v84 offset:10240
	ds_read_b128 v[136:139], v84 offset:10752
	s_nop 0
	v_max3_f32 v84, v48, v64, v49
	v_max3_f32 v85, v65, v50, v66
	v_max3_f32 v84, v84, v51, v67
	v_max3_f32 v85, v85, v52, v68
	v_max3_f32 v84, v84, v53, v69
	v_max3_f32 v85, v85, v54, v70
	v_max3_f32 v84, v84, v55, v71
	v_max3_f32 v85, v85, v56, v72
	v_max3_f32 v84, v84, v57, v73
	v_max3_f32 v85, v85, v58, v74
	v_max3_f32 v84, v84, v59, v75
	v_max3_f32 v85, v85, v60, v76
	v_max3_f32 v84, v84, v61, v77
	v_max3_f32 v85, v85, v62, v78
	v_max3_f32 v84, v84, v63, v79
	v_max_f32_e32 v85, v85, v85
	v_max_f32_e32 v84, v84, v84
	v_max_f32_e32 v84, v84, v85
	v_mov_b32_e32 v85, v84
	s_nop 1
	v_permlane32_swap_b32_e32 v84, v85
	v_max_f32_e32 v85, v85, v85
	v_max_f32_e32 v84, v84, v84
	v_max_f32_e32 v84, v84, v85
	v_cmp_lt_f32_e32 vcc, s97, v84
	v_cmp_lg_f32_e64 s[4:5], s96, v84
	s_nop 0
	v_cndmask_b32_e64 v85, 0, 1, vcc
	v_cndmask_b32_e64 v86, 0, 1, s[4:5]
	v_cndmask_b32_e64 v85, v86, v85, s[2:3]
	v_and_b32_e32 v85, 1, v85
	v_cmp_eq_u32_e64 s[6:7], 1, v85
	v_cmp_ne_u32_e32 vcc, 0, v85
	s_cbranch_vccz .LBB0_721
	v_cndmask_b32_e64 v32, 0, v84, s[6:7]
	v_exp_f32_e64 v34, -v32
	s_or_b64 s[4:5], s[2:3], s[4:5]
	v_add_f32_e32 v197, v197, v32
	v_pk_add_f32 v[48:49], v[48:49], v[32:33] op_sel_hi:[1,0] neg_lo:[0,1] neg_hi:[0,1]
	v_pk_add_f32 v[64:65], v[64:65], v[32:33] op_sel_hi:[1,0] neg_lo:[0,1] neg_hi:[0,1]
	v_pk_add_f32 v[50:51], v[50:51], v[32:33] op_sel_hi:[1,0] neg_lo:[0,1] neg_hi:[0,1]
	v_pk_add_f32 v[66:67], v[66:67], v[32:33] op_sel_hi:[1,0] neg_lo:[0,1] neg_hi:[0,1]
	v_pk_add_f32 v[52:53], v[52:53], v[32:33] op_sel_hi:[1,0] neg_lo:[0,1] neg_hi:[0,1]
	v_pk_add_f32 v[68:69], v[68:69], v[32:33] op_sel_hi:[1,0] neg_lo:[0,1] neg_hi:[0,1]
	v_pk_add_f32 v[54:55], v[54:55], v[32:33] op_sel_hi:[1,0] neg_lo:[0,1] neg_hi:[0,1]
	v_pk_add_f32 v[70:71], v[70:71], v[32:33] op_sel_hi:[1,0] neg_lo:[0,1] neg_hi:[0,1]
	v_pk_add_f32 v[56:57], v[56:57], v[32:33] op_sel_hi:[1,0] neg_lo:[0,1] neg_hi:[0,1]
	v_pk_add_f32 v[72:73], v[72:73], v[32:33] op_sel_hi:[1,0] neg_lo:[0,1] neg_hi:[0,1]
	v_pk_add_f32 v[58:59], v[58:59], v[32:33] op_sel_hi:[1,0] neg_lo:[0,1] neg_hi:[0,1]
	v_pk_add_f32 v[74:75], v[74:75], v[32:33] op_sel_hi:[1,0] neg_lo:[0,1] neg_hi:[0,1]
	v_pk_add_f32 v[60:61], v[60:61], v[32:33] op_sel_hi:[1,0] neg_lo:[0,1] neg_hi:[0,1]
	v_pk_add_f32 v[76:77], v[76:77], v[32:33] op_sel_hi:[1,0] neg_lo:[0,1] neg_hi:[0,1]
	v_pk_add_f32 v[62:63], v[62:63], v[32:33] op_sel_hi:[1,0] neg_lo:[0,1] neg_hi:[0,1]
	v_pk_add_f32 v[78:79], v[78:79], v[32:33] op_sel_hi:[1,0] neg_lo:[0,1] neg_hi:[0,1]
	v_xor_b32_e32 v32, 0x80000000, v197
	s_andn2_b64 s[2:3], s[2:3], exec
	s_and_b64 s[4:5], s[4:5], exec
	v_mul_f32_e32 v198, v198, v34
	v_pk_mul_f32 v[30:31], v[30:31], v[34:35] op_sel_hi:[1,0]
	v_pk_mul_f32 v[28:29], v[28:29], v[34:35] op_sel_hi:[1,0]
	v_pk_mul_f32 v[26:27], v[26:27], v[34:35] op_sel_hi:[1,0]
	v_pk_mul_f32 v[24:25], v[24:25], v[34:35] op_sel_hi:[1,0]
	v_pk_mul_f32 v[22:23], v[22:23], v[34:35] op_sel_hi:[1,0]
	v_pk_mul_f32 v[20:21], v[20:21], v[34:35] op_sel_hi:[1,0]
	v_pk_mul_f32 v[18:19], v[18:19], v[34:35] op_sel_hi:[1,0]
	v_pk_mul_f32 v[16:17], v[16:17], v[34:35] op_sel_hi:[1,0]
	v_pk_mul_f32 v[14:15], v[14:15], v[34:35] op_sel_hi:[1,0]
	v_pk_mul_f32 v[12:13], v[12:13], v[34:35] op_sel_hi:[1,0]
	v_pk_mul_f32 v[10:11], v[10:11], v[34:35] op_sel_hi:[1,0]
	v_pk_mul_f32 v[8:9], v[8:9], v[34:35] op_sel_hi:[1,0]
	v_pk_mul_f32 v[6:7], v[6:7], v[34:35] op_sel_hi:[1,0]
	v_pk_mul_f32 v[4:5], v[4:5], v[34:35] op_sel_hi:[1,0]
	v_pk_mul_f32 v[2:3], v[2:3], v[34:35] op_sel_hi:[1,0]
	v_pk_mul_f32 v[0:1], v[0:1], v[34:35] op_sel_hi:[1,0]
	v_mov_b32_e32 v33, v32
	v_mov_b32_e32 v34, v32
	v_mov_b32_e32 v35, v32
	v_mov_b32_e32 v36, v32
	v_mov_b32_e32 v37, v32
	v_mov_b32_e32 v38, v32
	v_mov_b32_e32 v39, v32
	v_mov_b32_e32 v40, v32
	v_mov_b32_e32 v41, v32
	v_mov_b32_e32 v42, v32
	v_mov_b32_e32 v43, v32
	v_mov_b32_e32 v44, v32
	v_mov_b32_e32 v45, v32
	v_mov_b32_e32 v46, v32
	v_mov_b32_e32 v47, v32
	s_or_b64 s[2:3], s[2:3], s[4:5]
.LBB0_721:
	s_mul_hi_u32 s5, s21, 0xaaaaaaab
	s_lshr_b32 s5, s5, 1
	s_add_i32 s4, s19, -4
	s_mul_i32 s5, s5, 0xffff1000
	s_waitcnt lgkmcnt(0)
	v_mfma_f32_32x32x16_bf16 v[96:111], v[80:83], v[112:115], v[32:47]
	v_exp_f32_e32 v48, v48
	v_exp_f32_e32 v49, v49
	v_exp_f32_e32 v50, v50
	v_exp_f32_e32 v51, v51
	v_exp_f32_e32 v52, v52
	v_exp_f32_e32 v53, v53
	v_exp_f32_e32 v54, v54
	v_mfma_f32_32x32x16_bf16 v[80:95], v[176:179], v[112:115], v[32:47]
	v_add_u32_e32 v176, s5, v195
	v_exp_f32_e32 v55, v55
	v_exp_f32_e32 v56, v56
	v_exp_f32_e32 v57, v57
	v_exp_f32_e32 v58, v58
	v_exp_f32_e32 v59, v59
	v_exp_f32_e32 v60, v60
	v_mfma_f32_32x32x16_bf16 v[96:111], v[168:171], v[116:119], v[96:111]
	v_exp_f32_e32 v61, v61
	v_exp_f32_e32 v62, v62
	v_exp_f32_e32 v63, v63
	v_mfma_f32_32x32x16_bf16 v[96:111], v[172:175], v[120:123], v[96:111]
	ds_read_b64_tr_b16 v[168:169], v176 offset:12288
	ds_read_b64_tr_b16 v[170:171], v176 offset:12800
	ds_read_b64_tr_b16 v[172:173], v176 offset:13312
	ds_read_b64_tr_b16 v[174:175], v176 offset:13824
	v_mfma_f32_32x32x16_bf16 v[80:95], v[152:155], v[116:119], v[80:95]
	v_mfma_f32_32x32x16_bf16 v[96:111], v[164:167], v[124:127], v[96:111]
	v_mfma_f32_32x32x16_bf16 v[80:95], v[148:151], v[120:123], v[80:95]
	v_mfma_f32_32x32x16_bf16 v[96:111], v[160:163], v[128:131], v[96:111]
	v_mfma_f32_32x32x16_bf16 v[80:95], v[144:147], v[124:127], v[80:95]
	v_mfma_f32_32x32x16_bf16 v[96:111], v[156:159], v[132:135], v[96:111]
	ds_read_b64_tr_b16 v[156:157], v176 offset:16384
	ds_read_b64_tr_b16 v[158:159], v176 offset:16896
	ds_read_b64_tr_b16 v[160:161], v176 offset:17408
	ds_read_b64_tr_b16 v[162:163], v176 offset:17920
	s_nop 1
	s_nop 0
	v_add_f32_e32 v164, v215, v48
	v_add_f32_e32 v165, v215, v49
	v_cvt_pk_bf16_f32 v144, v48, v49
	v_add_f32_e32 v152, v164, v50
	v_mfma_f32_32x32x16_bf16 v[80:95], v[140:143], v[128:131], v[80:95]
	v_add_f32_e32 v153, v165, v51
	v_add_f32_e32 v152, v152, v52
	v_cvt_pk_bf16_f32 v145, v50, v51
	v_add_f32_e32 v153, v153, v53
	v_add_f32_e32 v152, v152, v54
	v_cvt_pk_bf16_f32 v146, v52, v53
	v_add_f32_e32 v153, v153, v55
	v_add_f32_e32 v152, v152, v56
	v_cvt_pk_bf16_f32 v147, v54, v55
	v_add_f32_e32 v148, v153, v57
	v_add_f32_e32 v149, v152, v58
	v_cvt_pk_bf16_f32 v150, v60, v61
	v_add_f32_e32 v148, v148, v59
	v_add_f32_e32 v149, v149, v60
	v_cvt_pk_bf16_f32 v151, v62, v63
	v_add_f32_e32 v148, v148, v61
	v_add_f32_e32 v164, v149, v62
	v_cvt_pk_bf16_f32 v149, v58, v59
	v_add_f32_e32 v165, v148, v63
	v_cvt_pk_bf16_f32 v148, v56, v57
	s_waitcnt lgkmcnt(0)
	v_mfma_f32_32x32x16_bf16 v[0:15], v[168:171], v[144:147], v[0:15]
	v_exp_f32_e32 v64, v64
	v_exp_f32_e32 v65, v65
	v_exp_f32_e32 v66, v66
	v_exp_f32_e32 v67, v67
	v_exp_f32_e32 v68, v68
	v_exp_f32_e32 v69, v69
	v_exp_f32_e32 v70, v70
	v_mfma_f32_32x32x16_bf16 v[16:31], v[156:159], v[144:147], v[16:31]
	v_exp_f32_e32 v71, v71
	v_exp_f32_e32 v72, v72
	v_exp_f32_e32 v73, v73
	v_exp_f32_e32 v74, v74
	v_exp_f32_e32 v75, v75
	v_exp_f32_e32 v76, v76
	v_exp_f32_e32 v77, v77
	v_mfma_f32_32x32x16_bf16 v[0:15], v[172:175], v[148:151], v[0:15]
	v_exp_f32_e32 v78, v78
	v_exp_f32_e32 v79, v79
	v_mfma_f32_32x32x16_bf16 v[16:31], v[160:163], v[148:151], v[16:31]
	ds_read_b64_tr_b16 v[140:141], v176 offset:14336
	ds_read_b64_tr_b16 v[142:143], v176 offset:14848
	ds_read_b64_tr_b16 v[144:145], v176 offset:18432
	ds_read_b64_tr_b16 v[146:147], v176 offset:18944
	ds_read_b64_tr_b16 v[148:149], v176 offset:15360
	ds_read_b64_tr_b16 v[150:151], v176 offset:15872
	ds_read_b64_tr_b16 v[152:153], v176 offset:19456
	ds_read_b64_tr_b16 v[154:155], v176 offset:19968
	s_nop 1
	s_nop 0
	v_add_f32_e32 v156, v164, v64
	v_add_f32_e32 v157, v165, v65
	v_cvt_pk_bf16_f32 v158, v68, v69
	v_add_f32_e32 v156, v156, v66
	v_add_f32_e32 v157, v157, v67
	v_cvt_pk_bf16_f32 v159, v70, v71
	v_add_f32_e32 v156, v156, v68
	v_add_f32_e32 v157, v157, v69
	v_cvt_pk_bf16_f32 v160, v72, v73
	v_add_f32_e32 v156, v156, v70
	v_add_f32_e32 v157, v157, v71
	v_cvt_pk_bf16_f32 v161, v74, v75
	v_add_f32_e32 v156, v156, v72
	v_add_f32_e32 v157, v157, v73
	v_cvt_pk_bf16_f32 v162, v76, v77
	v_add_f32_e32 v156, v156, v74
	v_add_f32_e32 v157, v157, v75
	v_cvt_pk_bf16_f32 v163, v78, v79
	v_add_f32_e32 v156, v156, v76
	v_add_f32_e32 v157, v157, v77
	v_add_f32_e32 v164, v156, v78
	v_add_f32_e32 v165, v157, v79
	v_cvt_pk_bf16_f32 v156, v64, v65
	s_nop 0
	v_cvt_pk_bf16_f32 v157, v66, v67
	v_add_f32_e32 v164, v164, v165
	s_waitcnt lgkmcnt(0)
	v_mfma_f32_32x32x16_bf16 v[0:15], v[140:143], v[156:159], v[0:15]
	s_waitcnt vmcnt(3) lgkmcnt(0)
	s_barrier
	v_add_f32_e32 v198, v198, v164
	s_cmp_ge_u32 s4, s22
	v_mfma_f32_32x32x16_bf16 v[16:31], v[144:147], v[156:159], v[16:31]
	v_mfma_f32_32x32x16_bf16 v[0:15], v[148:151], v[160:163], v[0:15]
	v_mfma_f32_32x32x16_bf16 v[16:31], v[152:155], v[160:163], v[16:31]
	v_mfma_f32_32x32x16_bf16 v[80:95], v[136:139], v[132:135], v[80:95]
	s_cbranch_scc1 .LBB0_716
	s_min_u32 s4, s19, s22
	s_mul_hi_u32 s5, s4, 0x55555556
	s_mul_i32 s5, s5, 3
	s_sub_i32 s5, s4, s5
	s_mulk_i32 s5, 0x5000
	s_add_i32 s5, s5, 0
	s_mul_i32 s80, s4, 0xc000
	v_lshl_add_u64 v[48:49], v[184:185], 0, s[80:81]
	s_add_i32 m0, s5, s63
	s_add_i32 s4, s45, s95
	global_load_lds_dwordx4 v[48:49], off
	v_lshl_add_u64 v[48:49], v[186:187], 0, s[80:81]
	s_add_i32 m0, s5, s75
	s_lshl_b32 s80, s44, 15
	global_load_lds_dwordx4 v[48:49], off
	v_lshl_add_u64 v[48:49], v[188:189], 0, s[80:81]
	s_add_i32 m0, s4, 0x3000
	s_cmp_le_u32 s23, s39
	global_load_lds_dwordx4 v[48:49], off
	s_cbranch_scc1 .LBB0_724
	v_subrev_u32_e32 v48, 64, v196
	v_cmp_lt_i32_e32 vcc, -1, v48
	s_nop 1
	v_cndmask_b32_e32 v96, v249, v96, vcc
	v_cmp_lt_i32_e32 vcc, 31, v48
	s_nop 1
	v_cndmask_b32_e32 v80, v249, v80, vcc
	v_cmp_lt_i32_e32 vcc, 0, v48
	s_nop 1
	v_cndmask_b32_e32 v97, v249, v97, vcc
	v_cmp_lt_i32_e32 vcc, 32, v48
	s_nop 1
	v_cndmask_b32_e32 v81, v249, v81, vcc
	v_cmp_lt_i32_e32 vcc, 1, v48
	s_nop 1
	v_cndmask_b32_e32 v98, v249, v98, vcc
	v_cmp_lt_i32_e32 vcc, 33, v48
	s_nop 1
	v_cndmask_b32_e32 v82, v249, v82, vcc
	v_cmp_lt_i32_e32 vcc, 2, v48
	s_nop 1
	v_cndmask_b32_e32 v99, v249, v99, vcc
	v_cmp_lt_i32_e32 vcc, 34, v48
	s_nop 1
	v_cndmask_b32_e32 v83, v249, v83, vcc
	v_cmp_lt_i32_e32 vcc, 7, v48
	s_nop 1
	v_cndmask_b32_e32 v100, v249, v100, vcc
	v_cmp_lt_i32_e32 vcc, 39, v48
	s_nop 1
	v_cndmask_b32_e32 v84, v249, v84, vcc
	v_cmp_lt_i32_e32 vcc, 8, v48
	s_nop 1
	v_cndmask_b32_e32 v101, v249, v101, vcc
	v_cmp_lt_i32_e32 vcc, 40, v48
	s_nop 1
	v_cndmask_b32_e32 v85, v249, v85, vcc
	v_cmp_lt_i32_e32 vcc, 9, v48
	s_nop 1
	v_cndmask_b32_e32 v102, v249, v102, vcc
	v_cmp_lt_i32_e32 vcc, 41, v48
	s_nop 1
	v_cndmask_b32_e32 v86, v249, v86, vcc
	v_cmp_lt_i32_e32 vcc, 10, v48
	s_nop 1
	v_cndmask_b32_e32 v103, v249, v103, vcc
	v_cmp_lt_i32_e32 vcc, 42, v48
	s_nop 1
	v_cndmask_b32_e32 v87, v249, v87, vcc
	v_cmp_lt_i32_e32 vcc, 15, v48
	s_nop 1
	v_cndmask_b32_e32 v104, v249, v104, vcc
	v_cmp_lt_i32_e32 vcc, 47, v48
	s_nop 1
	v_cndmask_b32_e32 v88, v249, v88, vcc
	v_cmp_lt_i32_e32 vcc, 16, v48
	s_nop 1
	v_cndmask_b32_e32 v105, v249, v105, vcc
	v_cmp_lt_i32_e32 vcc, 48, v48
	s_nop 1
	v_cndmask_b32_e32 v89, v249, v89, vcc
	v_cmp_lt_i32_e32 vcc, 17, v48
	s_nop 1
	v_cndmask_b32_e32 v106, v249, v106, vcc
	v_cmp_lt_i32_e32 vcc, 49, v48
	s_nop 1
	v_cndmask_b32_e32 v90, v249, v90, vcc
	v_cmp_lt_i32_e32 vcc, 18, v48
	s_nop 1
	v_cndmask_b32_e32 v107, v249, v107, vcc
	v_cmp_lt_i32_e32 vcc, 50, v48
	s_nop 1
	v_cndmask_b32_e32 v91, v249, v91, vcc
	v_cmp_lt_i32_e32 vcc, 23, v48
	s_nop 1
	v_cndmask_b32_e32 v108, v249, v108, vcc
	v_cmp_lt_i32_e32 vcc, 55, v48
	s_nop 1
	v_cndmask_b32_e32 v92, v249, v92, vcc
	v_cmp_lt_i32_e32 vcc, 24, v48
	s_nop 1
	v_cndmask_b32_e32 v109, v249, v109, vcc
	v_cmp_lt_i32_e32 vcc, 56, v48
	s_nop 1
	v_cndmask_b32_e32 v93, v249, v93, vcc
	v_cmp_lt_i32_e32 vcc, 25, v48
	s_nop 1
	v_cndmask_b32_e32 v110, v249, v110, vcc
	v_cmp_lt_i32_e32 vcc, 57, v48
	s_nop 1
	v_cndmask_b32_e32 v94, v249, v94, vcc
	v_cmp_lt_i32_e32 vcc, 26, v48
	s_nop 1
	v_cndmask_b32_e32 v111, v249, v111, vcc
	v_cmp_lt_i32_e32 vcc, 58, v48
	s_nop 1
	v_cndmask_b32_e32 v95, v249, v95, vcc
.LBB0_724:
	v_add3_u32 v48, s43, v192, v193
	ds_read_b128 v[64:67], v48
	ds_read_b128 v[176:179], v48 offset:512
	ds_read_b128 v[168:171], v48 offset:2048
	ds_read_b128 v[152:155], v48 offset:2560
	ds_read_b128 v[172:175], v48 offset:4096
	ds_read_b128 v[148:151], v48 offset:4608
	ds_read_b128 v[164:167], v48 offset:6144
	ds_read_b128 v[144:147], v48 offset:6656
	ds_read_b128 v[160:163], v48 offset:8192
	ds_read_b128 v[140:143], v48 offset:8704
	ds_read_b128 v[156:159], v48 offset:10240
	ds_read_b128 v[136:139], v48 offset:10752
	s_nop 0
	v_max3_f32 v48, v96, v80, v97
	v_max3_f32 v49, v81, v98, v82
	v_max3_f32 v48, v48, v99, v83
	v_max3_f32 v49, v49, v100, v84
	v_max3_f32 v48, v48, v101, v85
	v_max3_f32 v49, v49, v102, v86
	v_max3_f32 v48, v48, v103, v87
	v_max3_f32 v49, v49, v104, v88
	v_max3_f32 v48, v48, v105, v89
	v_max3_f32 v49, v49, v106, v90
	v_max3_f32 v48, v48, v107, v91
	v_max3_f32 v49, v49, v108, v92
	v_max3_f32 v48, v48, v109, v93
	v_max3_f32 v49, v49, v110, v94
	v_max3_f32 v48, v48, v111, v95
	v_max_f32_e32 v49, v49, v49
	v_max_f32_e32 v48, v48, v48
	v_max_f32_e32 v48, v48, v49
	v_mov_b32_e32 v49, v48
	s_nop 1
	v_permlane32_swap_b32_e32 v48, v49
	v_max_f32_e32 v49, v49, v49
	v_max_f32_e32 v48, v48, v48
	v_max_f32_e32 v48, v48, v49
	v_cmp_lt_f32_e32 vcc, s97, v48
	v_cmp_lg_f32_e64 s[4:5], s96, v48
	s_nop 0
	v_cndmask_b32_e64 v49, 0, 1, vcc
	v_cndmask_b32_e64 v50, 0, 1, s[4:5]
	v_cndmask_b32_e64 v49, v50, v49, s[2:3]
	v_and_b32_e32 v49, 1, v49
	v_cmp_eq_u32_e64 s[6:7], 1, v49
	v_cmp_ne_u32_e32 vcc, 0, v49
	s_cbranch_vccz .LBB0_715
	v_cndmask_b32_e64 v32, 0, v48, s[6:7]
	v_exp_f32_e64 v34, -v32
	s_or_b64 s[4:5], s[2:3], s[4:5]
	v_add_f32_e32 v197, v197, v32
	v_pk_add_f32 v[96:97], v[96:97], v[32:33] op_sel_hi:[1,0] neg_lo:[0,1] neg_hi:[0,1]
	v_pk_add_f32 v[80:81], v[80:81], v[32:33] op_sel_hi:[1,0] neg_lo:[0,1] neg_hi:[0,1]
	v_pk_add_f32 v[98:99], v[98:99], v[32:33] op_sel_hi:[1,0] neg_lo:[0,1] neg_hi:[0,1]
	v_pk_add_f32 v[82:83], v[82:83], v[32:33] op_sel_hi:[1,0] neg_lo:[0,1] neg_hi:[0,1]
	v_pk_add_f32 v[100:101], v[100:101], v[32:33] op_sel_hi:[1,0] neg_lo:[0,1] neg_hi:[0,1]
	v_pk_add_f32 v[84:85], v[84:85], v[32:33] op_sel_hi:[1,0] neg_lo:[0,1] neg_hi:[0,1]
	v_pk_add_f32 v[102:103], v[102:103], v[32:33] op_sel_hi:[1,0] neg_lo:[0,1] neg_hi:[0,1]
	v_pk_add_f32 v[86:87], v[86:87], v[32:33] op_sel_hi:[1,0] neg_lo:[0,1] neg_hi:[0,1]
	v_pk_add_f32 v[104:105], v[104:105], v[32:33] op_sel_hi:[1,0] neg_lo:[0,1] neg_hi:[0,1]
	v_pk_add_f32 v[88:89], v[88:89], v[32:33] op_sel_hi:[1,0] neg_lo:[0,1] neg_hi:[0,1]
	v_pk_add_f32 v[106:107], v[106:107], v[32:33] op_sel_hi:[1,0] neg_lo:[0,1] neg_hi:[0,1]
	v_pk_add_f32 v[90:91], v[90:91], v[32:33] op_sel_hi:[1,0] neg_lo:[0,1] neg_hi:[0,1]
	v_pk_add_f32 v[108:109], v[108:109], v[32:33] op_sel_hi:[1,0] neg_lo:[0,1] neg_hi:[0,1]
	v_pk_add_f32 v[92:93], v[92:93], v[32:33] op_sel_hi:[1,0] neg_lo:[0,1] neg_hi:[0,1]
	v_pk_add_f32 v[110:111], v[110:111], v[32:33] op_sel_hi:[1,0] neg_lo:[0,1] neg_hi:[0,1]
	v_pk_add_f32 v[94:95], v[94:95], v[32:33] op_sel_hi:[1,0] neg_lo:[0,1] neg_hi:[0,1]
	v_xor_b32_e32 v32, 0x80000000, v197
	s_andn2_b64 s[2:3], s[2:3], exec
	s_and_b64 s[4:5], s[4:5], exec
	v_mul_f32_e32 v198, v198, v34
	v_pk_mul_f32 v[30:31], v[30:31], v[34:35] op_sel_hi:[1,0]
	v_pk_mul_f32 v[28:29], v[28:29], v[34:35] op_sel_hi:[1,0]
	v_pk_mul_f32 v[26:27], v[26:27], v[34:35] op_sel_hi:[1,0]
	v_pk_mul_f32 v[24:25], v[24:25], v[34:35] op_sel_hi:[1,0]
	v_pk_mul_f32 v[22:23], v[22:23], v[34:35] op_sel_hi:[1,0]
	v_pk_mul_f32 v[20:21], v[20:21], v[34:35] op_sel_hi:[1,0]
	v_pk_mul_f32 v[18:19], v[18:19], v[34:35] op_sel_hi:[1,0]
	v_pk_mul_f32 v[16:17], v[16:17], v[34:35] op_sel_hi:[1,0]
	v_pk_mul_f32 v[14:15], v[14:15], v[34:35] op_sel_hi:[1,0]
	v_pk_mul_f32 v[12:13], v[12:13], v[34:35] op_sel_hi:[1,0]
	v_pk_mul_f32 v[10:11], v[10:11], v[34:35] op_sel_hi:[1,0]
	v_pk_mul_f32 v[8:9], v[8:9], v[34:35] op_sel_hi:[1,0]
	v_pk_mul_f32 v[6:7], v[6:7], v[34:35] op_sel_hi:[1,0]
	v_pk_mul_f32 v[4:5], v[4:5], v[34:35] op_sel_hi:[1,0]
	v_pk_mul_f32 v[2:3], v[2:3], v[34:35] op_sel_hi:[1,0]
	v_pk_mul_f32 v[0:1], v[0:1], v[34:35] op_sel_hi:[1,0]
	v_mov_b32_e32 v33, v32
	v_mov_b32_e32 v34, v32
	v_mov_b32_e32 v35, v32
	v_mov_b32_e32 v36, v32
	v_mov_b32_e32 v37, v32
	v_mov_b32_e32 v38, v32
	v_mov_b32_e32 v39, v32
	v_mov_b32_e32 v40, v32
	v_mov_b32_e32 v41, v32
	v_mov_b32_e32 v42, v32
	v_mov_b32_e32 v43, v32
	v_mov_b32_e32 v44, v32
	v_mov_b32_e32 v45, v32
	v_mov_b32_e32 v46, v32
	v_mov_b32_e32 v47, v32
	s_or_b64 s[2:3], s[2:3], s[4:5]
	s_branch .LBB0_715

.LBB0_734:
	s_add_i32 s4, s21, -3
	s_min_u32 s4, s4, s40
	s_mul_hi_u32 s5, s4, 0x55555556
	s_mul_i32 s5, s5, 3
	s_sub_i32 s4, s4, s5
	s_mulk_i32 s4, 0x3000
	v_add_u32_e32 v88, s4, v134
	ds_read_b128 v[84:87], v88
	ds_read_b128 v[124:127], v88 offset:512
	ds_read_b128 v[80:83], v88 offset:2048
	ds_read_b128 v[120:123], v88 offset:2560
	s_nop 0
	v_max3_f32 v88, v48, v64, v49
	v_max3_f32 v89, v65, v50, v66
	v_max3_f32 v88, v88, v51, v67
	v_max3_f32 v89, v89, v52, v68
	v_max3_f32 v88, v88, v53, v69
	v_max3_f32 v89, v89, v54, v70
	v_max3_f32 v88, v88, v55, v71
	v_max3_f32 v89, v89, v56, v72
	v_max3_f32 v88, v88, v57, v73
	v_max3_f32 v89, v89, v58, v74
	v_max3_f32 v88, v88, v59, v75
	v_max3_f32 v89, v89, v60, v76
	v_max3_f32 v88, v88, v61, v77
	v_max3_f32 v89, v89, v62, v78
	v_max3_f32 v88, v88, v63, v79
	v_max_f32_e32 v89, v89, v89
	v_max_f32_e32 v88, v88, v88
	v_max_f32_e32 v88, v88, v89
	v_mov_b32_e32 v89, v88
	s_nop 1
	v_permlane32_swap_b32_e32 v88, v89
	v_max_f32_e32 v89, v89, v89
	v_max_f32_e32 v88, v88, v88
	v_max_f32_e32 v88, v88, v89
	v_cmp_lt_f32_e32 vcc, s97, v88
	v_cmp_lg_f32_e64 s[4:5], s96, v88
	s_nop 0
	v_cndmask_b32_e64 v89, 0, 1, vcc
	v_cndmask_b32_e64 v90, 0, 1, s[4:5]
	v_cndmask_b32_e64 v89, v90, v89, s[2:3]
	v_and_b32_e32 v89, 1, v89
	v_cmp_eq_u32_e64 s[6:7], 1, v89
	v_cmp_ne_u32_e32 vcc, 0, v89
	s_cbranch_vccz .LBB0_736
	v_cndmask_b32_e64 v32, 0, v88, s[6:7]
	v_exp_f32_e64 v34, -v32
	s_or_b64 s[4:5], s[2:3], s[4:5]
	v_add_f32_e32 v137, v137, v32
	v_pk_add_f32 v[48:49], v[48:49], v[32:33] op_sel_hi:[1,0] neg_lo:[0,1] neg_hi:[0,1]
	v_pk_add_f32 v[64:65], v[64:65], v[32:33] op_sel_hi:[1,0] neg_lo:[0,1] neg_hi:[0,1]
	v_pk_add_f32 v[50:51], v[50:51], v[32:33] op_sel_hi:[1,0] neg_lo:[0,1] neg_hi:[0,1]
	v_pk_add_f32 v[66:67], v[66:67], v[32:33] op_sel_hi:[1,0] neg_lo:[0,1] neg_hi:[0,1]
	v_pk_add_f32 v[52:53], v[52:53], v[32:33] op_sel_hi:[1,0] neg_lo:[0,1] neg_hi:[0,1]
	v_pk_add_f32 v[68:69], v[68:69], v[32:33] op_sel_hi:[1,0] neg_lo:[0,1] neg_hi:[0,1]
	v_pk_add_f32 v[54:55], v[54:55], v[32:33] op_sel_hi:[1,0] neg_lo:[0,1] neg_hi:[0,1]
	v_pk_add_f32 v[70:71], v[70:71], v[32:33] op_sel_hi:[1,0] neg_lo:[0,1] neg_hi:[0,1]
	v_pk_add_f32 v[56:57], v[56:57], v[32:33] op_sel_hi:[1,0] neg_lo:[0,1] neg_hi:[0,1]
	v_pk_add_f32 v[72:73], v[72:73], v[32:33] op_sel_hi:[1,0] neg_lo:[0,1] neg_hi:[0,1]
	v_pk_add_f32 v[58:59], v[58:59], v[32:33] op_sel_hi:[1,0] neg_lo:[0,1] neg_hi:[0,1]
	v_pk_add_f32 v[74:75], v[74:75], v[32:33] op_sel_hi:[1,0] neg_lo:[0,1] neg_hi:[0,1]
	v_pk_add_f32 v[60:61], v[60:61], v[32:33] op_sel_hi:[1,0] neg_lo:[0,1] neg_hi:[0,1]
	v_pk_add_f32 v[76:77], v[76:77], v[32:33] op_sel_hi:[1,0] neg_lo:[0,1] neg_hi:[0,1]
	v_pk_add_f32 v[62:63], v[62:63], v[32:33] op_sel_hi:[1,0] neg_lo:[0,1] neg_hi:[0,1]
	v_pk_add_f32 v[78:79], v[78:79], v[32:33] op_sel_hi:[1,0] neg_lo:[0,1] neg_hi:[0,1]
	v_xor_b32_e32 v32, 0x80000000, v137
	s_andn2_b64 s[2:3], s[2:3], exec
	s_and_b64 s[4:5], s[4:5], exec
	v_mul_f32_e32 v138, v138, v34
	v_pk_mul_f32 v[30:31], v[30:31], v[34:35] op_sel_hi:[1,0]
	v_pk_mul_f32 v[28:29], v[28:29], v[34:35] op_sel_hi:[1,0]
	v_pk_mul_f32 v[26:27], v[26:27], v[34:35] op_sel_hi:[1,0]
	v_pk_mul_f32 v[24:25], v[24:25], v[34:35] op_sel_hi:[1,0]
	v_pk_mul_f32 v[22:23], v[22:23], v[34:35] op_sel_hi:[1,0]
	v_pk_mul_f32 v[20:21], v[20:21], v[34:35] op_sel_hi:[1,0]
	v_pk_mul_f32 v[18:19], v[18:19], v[34:35] op_sel_hi:[1,0]
	v_pk_mul_f32 v[16:17], v[16:17], v[34:35] op_sel_hi:[1,0]
	v_pk_mul_f32 v[14:15], v[14:15], v[34:35] op_sel_hi:[1,0]
	v_pk_mul_f32 v[12:13], v[12:13], v[34:35] op_sel_hi:[1,0]
	v_pk_mul_f32 v[10:11], v[10:11], v[34:35] op_sel_hi:[1,0]
	v_pk_mul_f32 v[8:9], v[8:9], v[34:35] op_sel_hi:[1,0]
	v_pk_mul_f32 v[6:7], v[6:7], v[34:35] op_sel_hi:[1,0]
	v_pk_mul_f32 v[4:5], v[4:5], v[34:35] op_sel_hi:[1,0]
	v_pk_mul_f32 v[2:3], v[2:3], v[34:35] op_sel_hi:[1,0]
	v_pk_mul_f32 v[0:1], v[0:1], v[34:35] op_sel_hi:[1,0]
	v_mov_b32_e32 v33, v32
	v_mov_b32_e32 v34, v32
	v_mov_b32_e32 v35, v32
	v_mov_b32_e32 v36, v32
	v_mov_b32_e32 v37, v32
	v_mov_b32_e32 v38, v32
	v_mov_b32_e32 v39, v32
	v_mov_b32_e32 v40, v32
	v_mov_b32_e32 v41, v32
	v_mov_b32_e32 v42, v32
	v_mov_b32_e32 v43, v32
	v_mov_b32_e32 v44, v32
	v_mov_b32_e32 v45, v32
	v_mov_b32_e32 v46, v32
	v_mov_b32_e32 v47, v32
	s_or_b64 s[2:3], s[2:3], s[4:5]
.LBB0_736:
	s_mul_hi_u32 s5, s44, 0xaaaaaaab
	s_lshr_b32 s5, s5, 1
	s_add_i32 s4, s21, -4
	s_mul_i32 s5, s5, 0xffff7000
	s_waitcnt lgkmcnt(0)
	v_mfma_f32_32x32x16_bf16 v[96:111], v[84:87], v[112:115], v[32:47]
	v_add_u32_e32 v139, s5, v135
	v_exp_f32_e32 v48, v48
	v_exp_f32_e32 v49, v49
	v_exp_f32_e32 v50, v50
	v_exp_f32_e32 v51, v51
	v_exp_f32_e32 v52, v52
	v_exp_f32_e32 v53, v53
	v_exp_f32_e32 v54, v54
	v_exp_f32_e32 v55, v55
	v_mfma_f32_32x32x16_bf16 v[96:111], v[80:83], v[116:119], v[96:111]
	v_exp_f32_e32 v56, v56
	v_exp_f32_e32 v57, v57
	v_exp_f32_e32 v58, v58
	v_exp_f32_e32 v59, v59
	v_exp_f32_e32 v60, v60
	v_exp_f32_e32 v61, v61
	v_exp_f32_e32 v62, v62
	v_exp_f32_e32 v63, v63
	v_mfma_f32_32x32x16_bf16 v[80:95], v[124:127], v[112:115], v[32:47]
	ds_read_b64_tr_b16 v[140:141], v139 offset:4096
	ds_read_b64_tr_b16 v[142:143], v139 offset:4608
	ds_read_b64_tr_b16 v[144:145], v139 offset:5120
	ds_read_b64_tr_b16 v[146:147], v139 offset:5632
	ds_read_b64_tr_b16 v[148:149], v139 offset:8192
	ds_read_b64_tr_b16 v[150:151], v139 offset:8704
	ds_read_b64_tr_b16 v[152:153], v139 offset:9216
	ds_read_b64_tr_b16 v[154:155], v139 offset:9728
	s_nop 1
	s_nop 0
	v_add_f32_e32 v124, v215, v48
	v_add_f32_e32 v125, v215, v49
	v_cvt_pk_bf16_f32 v126, v52, v53
	v_add_f32_e32 v124, v124, v50
	v_add_f32_e32 v125, v125, v51
	v_cvt_pk_bf16_f32 v127, v54, v55
	v_add_f32_e32 v124, v124, v52
	v_add_f32_e32 v125, v125, v53
	v_cvt_pk_bf16_f32 v156, v56, v57
	v_add_f32_e32 v124, v124, v54
	v_add_f32_e32 v125, v125, v55
	v_cvt_pk_bf16_f32 v157, v58, v59
	v_add_f32_e32 v124, v124, v56
	v_add_f32_e32 v125, v125, v57
	v_cvt_pk_bf16_f32 v158, v60, v61
	v_add_f32_e32 v124, v124, v58
	v_add_f32_e32 v125, v125, v59
	v_cvt_pk_bf16_f32 v159, v62, v63
	v_add_f32_e32 v124, v124, v60
	v_add_f32_e32 v125, v125, v61
	v_add_f32_e32 v160, v124, v62
	v_add_f32_e32 v161, v125, v63
	v_cvt_pk_bf16_f32 v124, v48, v49
	v_cvt_pk_bf16_f32 v125, v50, v51
	s_waitcnt lgkmcnt(0)
	s_nop 0
	v_mfma_f32_32x32x16_bf16 v[0:15], v[140:143], v[124:127], v[0:15]
	v_exp_f32_e32 v64, v64
	v_exp_f32_e32 v65, v65
	v_exp_f32_e32 v66, v66
	v_exp_f32_e32 v67, v67
	v_exp_f32_e32 v68, v68
	v_exp_f32_e32 v69, v69
	v_exp_f32_e32 v70, v70
	v_mfma_f32_32x32x16_bf16 v[16:31], v[148:151], v[124:127], v[16:31]
	v_exp_f32_e32 v71, v71
	v_exp_f32_e32 v72, v72
	v_exp_f32_e32 v73, v73
	v_exp_f32_e32 v74, v74
	v_exp_f32_e32 v75, v75
	v_exp_f32_e32 v76, v76
	v_exp_f32_e32 v77, v77
	v_mfma_f32_32x32x16_bf16 v[0:15], v[144:147], v[156:159], v[0:15]
	ds_read_b64_tr_b16 v[124:125], v139 offset:6144
	ds_read_b64_tr_b16 v[126:127], v139 offset:6656
	ds_read_b64_tr_b16 v[140:141], v139 offset:10240
	ds_read_b64_tr_b16 v[142:143], v139 offset:10752
	ds_read_b64_tr_b16 v[144:145], v139 offset:7168
	ds_read_b64_tr_b16 v[146:147], v139 offset:7680
	ds_read_b64_tr_b16 v[148:149], v139 offset:11264
	ds_read_b64_tr_b16 v[150:151], v139 offset:11776
	v_exp_f32_e32 v78, v78
	v_exp_f32_e32 v79, v79
	s_nop 1
	s_nop 0
	v_add_f32_e32 v139, v160, v64
	v_mfma_f32_32x32x16_bf16 v[16:31], v[152:155], v[156:159], v[16:31]
	v_add_f32_e32 v152, v161, v65
	v_add_f32_e32 v139, v139, v66
	v_cvt_pk_bf16_f32 v153, v66, v67
	v_add_f32_e32 v152, v152, v67
	v_add_f32_e32 v139, v139, v68
	v_cvt_pk_bf16_f32 v154, v68, v69
	v_add_f32_e32 v152, v152, v69
	v_add_f32_e32 v139, v139, v70
	v_cvt_pk_bf16_f32 v155, v70, v71
	v_add_f32_e32 v152, v152, v71
	v_add_f32_e32 v139, v139, v72
	v_cvt_pk_bf16_f32 v156, v72, v73
	v_add_f32_e32 v152, v152, v73
	v_add_f32_e32 v139, v139, v74
	v_cvt_pk_bf16_f32 v157, v74, v75
	v_add_f32_e32 v152, v152, v75
	v_add_f32_e32 v139, v139, v76
	v_cvt_pk_bf16_f32 v158, v76, v77
	v_add_f32_e32 v152, v152, v77
	v_add_f32_e32 v139, v139, v78
	v_cvt_pk_bf16_f32 v159, v78, v79
	v_add_f32_e32 v160, v152, v79
	v_cvt_pk_bf16_f32 v152, v64, v65
	s_nop 0
	s_nop 0
	v_add_f32_e32 v139, v139, v160
	s_waitcnt lgkmcnt(0)
	v_mfma_f32_32x32x16_bf16 v[0:15], v[124:127], v[152:155], v[0:15]
	s_waitcnt vmcnt(2) lgkmcnt(0)
	s_barrier
	v_add_f32_e32 v138, v138, v139
	s_cmp_ge_u32 s4, s40
	v_mfma_f32_32x32x16_bf16 v[16:31], v[140:143], v[152:155], v[16:31]
	v_mfma_f32_32x32x16_bf16 v[0:15], v[144:147], v[156:159], v[0:15]
	v_mfma_f32_32x32x16_bf16 v[16:31], v[148:151], v[156:159], v[16:31]
	v_mfma_f32_32x32x16_bf16 v[80:95], v[120:123], v[116:119], v[80:95]
	s_cbranch_scc1 .LBB0_731
	s_min_u32 s4, s21, s40
	s_mul_hi_u32 s5, s4, 0x55555556
	s_mul_i32 s5, s5, 3
	s_sub_i32 s5, s4, s5
	s_mul_i32 s6, s5, 0x3000
	s_mul_i32 s4, s4, 0x50000
	s_mov_b32 s5, s81
	v_lshl_add_u64 v[48:49], v[128:129], 0, s[4:5]
	v_lshl_add_u64 v[48:49], v[48:49], 0, s[76:77]
	s_add_i32 m0, s93, s6
	s_add_i32 s4, s48, s95
	global_load_lds_dwordx4 v[48:49], off
	v_lshl_add_u64 v[48:49], v[130:131], 0, s[80:81]
	v_lshl_add_u64 v[48:49], v[48:49], 0, s[0:1]
	s_add_i32 m0, s4, 0x1000
	s_cmp_le_u32 s45, s39
	global_load_lds_dwordx4 v[48:49], off
	s_cbranch_scc1 .LBB0_739
	v_subrev_u32_e32 v48, 64, v136
	v_cmp_lt_i32_e32 vcc, -1, v48
	s_nop 1
	v_cndmask_b32_e32 v96, v249, v96, vcc
	v_cmp_lt_i32_e32 vcc, 31, v48
	s_nop 1
	v_cndmask_b32_e32 v80, v249, v80, vcc
	v_cmp_lt_i32_e32 vcc, 0, v48
	s_nop 1
	v_cndmask_b32_e32 v97, v249, v97, vcc
	v_cmp_lt_i32_e32 vcc, 32, v48
	s_nop 1
	v_cndmask_b32_e32 v81, v249, v81, vcc
	v_cmp_lt_i32_e32 vcc, 1, v48
	s_nop 1
	v_cndmask_b32_e32 v98, v249, v98, vcc
	v_cmp_lt_i32_e32 vcc, 33, v48
	s_nop 1
	v_cndmask_b32_e32 v82, v249, v82, vcc
	v_cmp_lt_i32_e32 vcc, 2, v48
	s_nop 1
	v_cndmask_b32_e32 v99, v249, v99, vcc
	v_cmp_lt_i32_e32 vcc, 34, v48
	s_nop 1
	v_cndmask_b32_e32 v83, v249, v83, vcc
	v_cmp_lt_i32_e32 vcc, 7, v48
	s_nop 1
	v_cndmask_b32_e32 v100, v249, v100, vcc
	v_cmp_lt_i32_e32 vcc, 39, v48
	s_nop 1
	v_cndmask_b32_e32 v84, v249, v84, vcc
	v_cmp_lt_i32_e32 vcc, 8, v48
	s_nop 1
	v_cndmask_b32_e32 v101, v249, v101, vcc
	v_cmp_lt_i32_e32 vcc, 40, v48
	s_nop 1
	v_cndmask_b32_e32 v85, v249, v85, vcc
	v_cmp_lt_i32_e32 vcc, 9, v48
	s_nop 1
	v_cndmask_b32_e32 v102, v249, v102, vcc
	v_cmp_lt_i32_e32 vcc, 41, v48
	s_nop 1
	v_cndmask_b32_e32 v86, v249, v86, vcc
	v_cmp_lt_i32_e32 vcc, 10, v48
	s_nop 1
	v_cndmask_b32_e32 v103, v249, v103, vcc
	v_cmp_lt_i32_e32 vcc, 42, v48
	s_nop 1
	v_cndmask_b32_e32 v87, v249, v87, vcc
	v_cmp_lt_i32_e32 vcc, 15, v48
	s_nop 1
	v_cndmask_b32_e32 v104, v249, v104, vcc
	v_cmp_lt_i32_e32 vcc, 47, v48
	s_nop 1
	v_cndmask_b32_e32 v88, v249, v88, vcc
	v_cmp_lt_i32_e32 vcc, 16, v48
	s_nop 1
	v_cndmask_b32_e32 v105, v249, v105, vcc
	v_cmp_lt_i32_e32 vcc, 48, v48
	s_nop 1
	v_cndmask_b32_e32 v89, v249, v89, vcc
	v_cmp_lt_i32_e32 vcc, 17, v48
	s_nop 1
	v_cndmask_b32_e32 v106, v249, v106, vcc
	v_cmp_lt_i32_e32 vcc, 49, v48
	s_nop 1
	v_cndmask_b32_e32 v90, v249, v90, vcc
	v_cmp_lt_i32_e32 vcc, 18, v48
	s_nop 1
	v_cndmask_b32_e32 v107, v249, v107, vcc
	v_cmp_lt_i32_e32 vcc, 50, v48
	s_nop 1
	v_cndmask_b32_e32 v91, v249, v91, vcc
	v_cmp_lt_i32_e32 vcc, 23, v48
	s_nop 1
	v_cndmask_b32_e32 v108, v249, v108, vcc
	v_cmp_lt_i32_e32 vcc, 55, v48
	s_nop 1
	v_cndmask_b32_e32 v92, v249, v92, vcc
	v_cmp_lt_i32_e32 vcc, 24, v48
	s_nop 1
	v_cndmask_b32_e32 v109, v249, v109, vcc
	v_cmp_lt_i32_e32 vcc, 56, v48
	s_nop 1
	v_cndmask_b32_e32 v93, v249, v93, vcc
	v_cmp_lt_i32_e32 vcc, 25, v48
	s_nop 1
	v_cndmask_b32_e32 v110, v249, v110, vcc
	v_cmp_lt_i32_e32 vcc, 57, v48
	s_nop 1
	v_cndmask_b32_e32 v94, v249, v94, vcc
	v_cmp_lt_i32_e32 vcc, 26, v48
	s_nop 1
	v_cndmask_b32_e32 v111, v249, v111, vcc
	v_cmp_lt_i32_e32 vcc, 58, v48
	s_nop 1
	v_cndmask_b32_e32 v95, v249, v95, vcc
.LBB0_739:
	v_add3_u32 v48, s47, v132, v133
	ds_read_b128 v[68:71], v48
	ds_read_b128 v[124:127], v48 offset:512
	ds_read_b128 v[64:67], v48 offset:2048
	ds_read_b128 v[120:123], v48 offset:2560
	s_nop 0
	v_max3_f32 v48, v96, v80, v97
	v_max3_f32 v49, v81, v98, v82
	v_max3_f32 v48, v48, v99, v83
	v_max3_f32 v49, v49, v100, v84
	v_max3_f32 v48, v48, v101, v85
	v_max3_f32 v49, v49, v102, v86
	v_max3_f32 v48, v48, v103, v87
	v_max3_f32 v49, v49, v104, v88
	v_max3_f32 v48, v48, v105, v89
	v_max3_f32 v49, v49, v106, v90
	v_max3_f32 v48, v48, v107, v91
	v_max3_f32 v49, v49, v108, v92
	v_max3_f32 v48, v48, v109, v93
	v_max3_f32 v49, v49, v110, v94
	v_max3_f32 v48, v48, v111, v95
	v_max_f32_e32 v49, v49, v49
	v_max_f32_e32 v48, v48, v48
	v_max_f32_e32 v48, v48, v49
	v_mov_b32_e32 v49, v48
	s_nop 1
	v_permlane32_swap_b32_e32 v48, v49
	v_max_f32_e32 v49, v49, v49
	v_max_f32_e32 v48, v48, v48
	v_max_f32_e32 v48, v48, v49
	v_cmp_lt_f32_e32 vcc, s97, v48
	v_cmp_lg_f32_e64 s[4:5], s96, v48
	s_nop 0
	v_cndmask_b32_e64 v49, 0, 1, vcc
	v_cndmask_b32_e64 v50, 0, 1, s[4:5]
	v_cndmask_b32_e64 v49, v50, v49, s[2:3]
	v_and_b32_e32 v49, 1, v49
	v_cmp_eq_u32_e64 s[6:7], 1, v49
	v_cmp_ne_u32_e32 vcc, 0, v49
	s_cbranch_vccz .LBB0_730
	v_cndmask_b32_e64 v32, 0, v48, s[6:7]
	v_exp_f32_e64 v34, -v32
	s_or_b64 s[4:5], s[2:3], s[4:5]
	v_add_f32_e32 v137, v137, v32
	v_pk_add_f32 v[96:97], v[96:97], v[32:33] op_sel_hi:[1,0] neg_lo:[0,1] neg_hi:[0,1]
	v_pk_add_f32 v[80:81], v[80:81], v[32:33] op_sel_hi:[1,0] neg_lo:[0,1] neg_hi:[0,1]
	v_pk_add_f32 v[98:99], v[98:99], v[32:33] op_sel_hi:[1,0] neg_lo:[0,1] neg_hi:[0,1]
	v_pk_add_f32 v[82:83], v[82:83], v[32:33] op_sel_hi:[1,0] neg_lo:[0,1] neg_hi:[0,1]
	v_pk_add_f32 v[100:101], v[100:101], v[32:33] op_sel_hi:[1,0] neg_lo:[0,1] neg_hi:[0,1]
	v_pk_add_f32 v[84:85], v[84:85], v[32:33] op_sel_hi:[1,0] neg_lo:[0,1] neg_hi:[0,1]
	v_pk_add_f32 v[102:103], v[102:103], v[32:33] op_sel_hi:[1,0] neg_lo:[0,1] neg_hi:[0,1]
	v_pk_add_f32 v[86:87], v[86:87], v[32:33] op_sel_hi:[1,0] neg_lo:[0,1] neg_hi:[0,1]
	v_pk_add_f32 v[104:105], v[104:105], v[32:33] op_sel_hi:[1,0] neg_lo:[0,1] neg_hi:[0,1]
	v_pk_add_f32 v[88:89], v[88:89], v[32:33] op_sel_hi:[1,0] neg_lo:[0,1] neg_hi:[0,1]
	v_pk_add_f32 v[106:107], v[106:107], v[32:33] op_sel_hi:[1,0] neg_lo:[0,1] neg_hi:[0,1]
	v_pk_add_f32 v[90:91], v[90:91], v[32:33] op_sel_hi:[1,0] neg_lo:[0,1] neg_hi:[0,1]
	v_pk_add_f32 v[108:109], v[108:109], v[32:33] op_sel_hi:[1,0] neg_lo:[0,1] neg_hi:[0,1]
	v_pk_add_f32 v[92:93], v[92:93], v[32:33] op_sel_hi:[1,0] neg_lo:[0,1] neg_hi:[0,1]
	v_pk_add_f32 v[110:111], v[110:111], v[32:33] op_sel_hi:[1,0] neg_lo:[0,1] neg_hi:[0,1]
	v_pk_add_f32 v[94:95], v[94:95], v[32:33] op_sel_hi:[1,0] neg_lo:[0,1] neg_hi:[0,1]
	v_xor_b32_e32 v32, 0x80000000, v137
	s_andn2_b64 s[2:3], s[2:3], exec
	s_and_b64 s[4:5], s[4:5], exec
	v_mul_f32_e32 v138, v138, v34
	v_pk_mul_f32 v[30:31], v[30:31], v[34:35] op_sel_hi:[1,0]
	v_pk_mul_f32 v[28:29], v[28:29], v[34:35] op_sel_hi:[1,0]
	v_pk_mul_f32 v[26:27], v[26:27], v[34:35] op_sel_hi:[1,0]
	v_pk_mul_f32 v[24:25], v[24:25], v[34:35] op_sel_hi:[1,0]
	v_pk_mul_f32 v[22:23], v[22:23], v[34:35] op_sel_hi:[1,0]
	v_pk_mul_f32 v[20:21], v[20:21], v[34:35] op_sel_hi:[1,0]
	v_pk_mul_f32 v[18:19], v[18:19], v[34:35] op_sel_hi:[1,0]
	v_pk_mul_f32 v[16:17], v[16:17], v[34:35] op_sel_hi:[1,0]
	v_pk_mul_f32 v[14:15], v[14:15], v[34:35] op_sel_hi:[1,0]
	v_pk_mul_f32 v[12:13], v[12:13], v[34:35] op_sel_hi:[1,0]
	v_pk_mul_f32 v[10:11], v[10:11], v[34:35] op_sel_hi:[1,0]
	v_pk_mul_f32 v[8:9], v[8:9], v[34:35] op_sel_hi:[1,0]
	v_pk_mul_f32 v[6:7], v[6:7], v[34:35] op_sel_hi:[1,0]
	v_pk_mul_f32 v[4:5], v[4:5], v[34:35] op_sel_hi:[1,0]
	v_pk_mul_f32 v[2:3], v[2:3], v[34:35] op_sel_hi:[1,0]
	v_pk_mul_f32 v[0:1], v[0:1], v[34:35] op_sel_hi:[1,0]
	v_mov_b32_e32 v33, v32
	v_mov_b32_e32 v34, v32
	v_mov_b32_e32 v35, v32
	v_mov_b32_e32 v36, v32
	v_mov_b32_e32 v37, v32
	v_mov_b32_e32 v38, v32
	v_mov_b32_e32 v39, v32
	v_mov_b32_e32 v40, v32
	v_mov_b32_e32 v41, v32
	v_mov_b32_e32 v42, v32
	v_mov_b32_e32 v43, v32
	v_mov_b32_e32 v44, v32
	v_mov_b32_e32 v45, v32
	v_mov_b32_e32 v46, v32
	v_mov_b32_e32 v47, v32
	s_or_b64 s[2:3], s[2:3], s[4:5]
	s_branch .LBB0_730

.LBB0_746:
	s_add_i32 s4, s17, -3
	s_min_u32 s4, s4, s40
	s_mul_hi_u32 s5, s4, 0x55555556
	s_mul_i32 s5, s5, 3
	s_sub_i32 s4, s4, s5
	s_mulk_i32 s4, 0x3000
	v_add_u32_e32 v88, s4, v135
	ds_read_b128 v[84:87], v88
	ds_read_b128 v[124:127], v88 offset:512
	ds_read_b128 v[80:83], v88 offset:2048
	ds_read_b128 v[120:123], v88 offset:2560
	s_nop 0
	v_max3_f32 v88, v48, v64, v49
	v_max3_f32 v89, v65, v50, v66
	v_max3_f32 v88, v88, v51, v67
	v_max3_f32 v89, v89, v52, v68
	v_max3_f32 v88, v88, v53, v69
	v_max3_f32 v89, v89, v54, v70
	v_max3_f32 v88, v88, v55, v71
	v_max3_f32 v89, v89, v56, v72
	v_max3_f32 v88, v88, v57, v73
	v_max3_f32 v89, v89, v58, v74
	v_max3_f32 v88, v88, v59, v75
	v_max3_f32 v89, v89, v60, v76
	v_max3_f32 v88, v88, v61, v77
	v_max3_f32 v89, v89, v62, v78
	v_max3_f32 v88, v88, v63, v79
	v_max_f32_e32 v89, v89, v89
	v_max_f32_e32 v88, v88, v88
	v_max_f32_e32 v88, v88, v89
	v_mov_b32_e32 v89, v88
	s_nop 1
	v_permlane32_swap_b32_e32 v88, v89
	v_max_f32_e32 v89, v89, v89
	v_max_f32_e32 v88, v88, v88
	v_max_f32_e32 v88, v88, v89
	v_cmp_lt_f32_e32 vcc, s97, v88
	v_cmp_lg_f32_e64 s[4:5], s96, v88
	s_nop 0
	v_cndmask_b32_e64 v89, 0, 1, vcc
	v_cndmask_b32_e64 v90, 0, 1, s[4:5]
	v_cndmask_b32_e64 v89, v90, v89, s[2:3]
	v_and_b32_e32 v89, 1, v89
	v_cmp_eq_u32_e64 s[6:7], 1, v89
	v_cmp_ne_u32_e32 vcc, 0, v89
	s_cbranch_vccz .LBB0_748
	v_cndmask_b32_e64 v32, 0, v88, s[6:7]
	v_exp_f32_e64 v34, -v32
	s_or_b64 s[4:5], s[2:3], s[4:5]
	v_add_f32_e32 v138, v138, v32
	v_pk_add_f32 v[48:49], v[48:49], v[32:33] op_sel_hi:[1,0] neg_lo:[0,1] neg_hi:[0,1]
	v_pk_add_f32 v[64:65], v[64:65], v[32:33] op_sel_hi:[1,0] neg_lo:[0,1] neg_hi:[0,1]
	v_pk_add_f32 v[50:51], v[50:51], v[32:33] op_sel_hi:[1,0] neg_lo:[0,1] neg_hi:[0,1]
	v_pk_add_f32 v[66:67], v[66:67], v[32:33] op_sel_hi:[1,0] neg_lo:[0,1] neg_hi:[0,1]
	v_pk_add_f32 v[52:53], v[52:53], v[32:33] op_sel_hi:[1,0] neg_lo:[0,1] neg_hi:[0,1]
	v_pk_add_f32 v[68:69], v[68:69], v[32:33] op_sel_hi:[1,0] neg_lo:[0,1] neg_hi:[0,1]
	v_pk_add_f32 v[54:55], v[54:55], v[32:33] op_sel_hi:[1,0] neg_lo:[0,1] neg_hi:[0,1]
	v_pk_add_f32 v[70:71], v[70:71], v[32:33] op_sel_hi:[1,0] neg_lo:[0,1] neg_hi:[0,1]
	v_pk_add_f32 v[56:57], v[56:57], v[32:33] op_sel_hi:[1,0] neg_lo:[0,1] neg_hi:[0,1]
	v_pk_add_f32 v[72:73], v[72:73], v[32:33] op_sel_hi:[1,0] neg_lo:[0,1] neg_hi:[0,1]
	v_pk_add_f32 v[58:59], v[58:59], v[32:33] op_sel_hi:[1,0] neg_lo:[0,1] neg_hi:[0,1]
	v_pk_add_f32 v[74:75], v[74:75], v[32:33] op_sel_hi:[1,0] neg_lo:[0,1] neg_hi:[0,1]
	v_pk_add_f32 v[60:61], v[60:61], v[32:33] op_sel_hi:[1,0] neg_lo:[0,1] neg_hi:[0,1]
	v_pk_add_f32 v[76:77], v[76:77], v[32:33] op_sel_hi:[1,0] neg_lo:[0,1] neg_hi:[0,1]
	v_pk_add_f32 v[62:63], v[62:63], v[32:33] op_sel_hi:[1,0] neg_lo:[0,1] neg_hi:[0,1]
	v_pk_add_f32 v[78:79], v[78:79], v[32:33] op_sel_hi:[1,0] neg_lo:[0,1] neg_hi:[0,1]
	v_xor_b32_e32 v32, 0x80000000, v138
	s_andn2_b64 s[2:3], s[2:3], exec
	s_and_b64 s[4:5], s[4:5], exec
	v_mul_f32_e32 v139, v139, v34
	v_pk_mul_f32 v[30:31], v[30:31], v[34:35] op_sel_hi:[1,0]
	v_pk_mul_f32 v[28:29], v[28:29], v[34:35] op_sel_hi:[1,0]
	v_pk_mul_f32 v[26:27], v[26:27], v[34:35] op_sel_hi:[1,0]
	v_pk_mul_f32 v[24:25], v[24:25], v[34:35] op_sel_hi:[1,0]
	v_pk_mul_f32 v[22:23], v[22:23], v[34:35] op_sel_hi:[1,0]
	v_pk_mul_f32 v[20:21], v[20:21], v[34:35] op_sel_hi:[1,0]
	v_pk_mul_f32 v[18:19], v[18:19], v[34:35] op_sel_hi:[1,0]
	v_pk_mul_f32 v[16:17], v[16:17], v[34:35] op_sel_hi:[1,0]
	v_pk_mul_f32 v[14:15], v[14:15], v[34:35] op_sel_hi:[1,0]
	v_pk_mul_f32 v[12:13], v[12:13], v[34:35] op_sel_hi:[1,0]
	v_pk_mul_f32 v[10:11], v[10:11], v[34:35] op_sel_hi:[1,0]
	v_pk_mul_f32 v[8:9], v[8:9], v[34:35] op_sel_hi:[1,0]
	v_pk_mul_f32 v[6:7], v[6:7], v[34:35] op_sel_hi:[1,0]
	v_pk_mul_f32 v[4:5], v[4:5], v[34:35] op_sel_hi:[1,0]
	v_pk_mul_f32 v[2:3], v[2:3], v[34:35] op_sel_hi:[1,0]
	v_pk_mul_f32 v[0:1], v[0:1], v[34:35] op_sel_hi:[1,0]
	v_mov_b32_e32 v33, v32
	v_mov_b32_e32 v34, v32
	v_mov_b32_e32 v35, v32
	v_mov_b32_e32 v36, v32
	v_mov_b32_e32 v37, v32
	v_mov_b32_e32 v38, v32
	v_mov_b32_e32 v39, v32
	v_mov_b32_e32 v40, v32
	v_mov_b32_e32 v41, v32
	v_mov_b32_e32 v42, v32
	v_mov_b32_e32 v43, v32
	v_mov_b32_e32 v44, v32
	v_mov_b32_e32 v45, v32
	v_mov_b32_e32 v46, v32
	v_mov_b32_e32 v47, v32
	s_or_b64 s[2:3], s[2:3], s[4:5]
.LBB0_748:
	s_mul_hi_u32 s5, s16, 0xaaaaaaab
	s_lshr_b32 s5, s5, 1
	s_add_i32 s4, s17, -4
	s_mul_i32 s5, s5, 0xffff7000
	s_waitcnt lgkmcnt(0)
	v_mfma_f32_32x32x16_bf16 v[96:111], v[84:87], v[112:115], v[32:47]
	v_add_u32_e32 v160, s5, v136
	v_exp_f32_e32 v48, v48
	v_exp_f32_e32 v49, v49
	v_exp_f32_e32 v50, v50
	v_exp_f32_e32 v51, v51
	v_exp_f32_e32 v52, v52
	v_exp_f32_e32 v53, v53
	v_exp_f32_e32 v54, v54
	v_exp_f32_e32 v55, v55
	v_mfma_f32_32x32x16_bf16 v[96:111], v[80:83], v[116:119], v[96:111]
	v_exp_f32_e32 v56, v56
	v_exp_f32_e32 v57, v57
	v_exp_f32_e32 v58, v58
	v_exp_f32_e32 v59, v59
	v_exp_f32_e32 v60, v60
	v_exp_f32_e32 v61, v61
	v_exp_f32_e32 v62, v62
	v_exp_f32_e32 v63, v63
	v_mfma_f32_32x32x16_bf16 v[80:95], v[124:127], v[112:115], v[32:47]
	ds_read_b64_tr_b16 v[140:141], v160 offset:4096
	ds_read_b64_tr_b16 v[142:143], v160 offset:4608
	ds_read_b64_tr_b16 v[144:145], v160 offset:5120
	ds_read_b64_tr_b16 v[146:147], v160 offset:5632
	ds_read_b64_tr_b16 v[148:149], v160 offset:8192
	ds_read_b64_tr_b16 v[150:151], v160 offset:8704
	ds_read_b64_tr_b16 v[152:153], v160 offset:9216
	ds_read_b64_tr_b16 v[154:155], v160 offset:9728
	s_nop 1
	s_nop 0
	v_add_f32_e32 v124, v215, v48
	v_add_f32_e32 v125, v215, v49
	v_cvt_pk_bf16_f32 v126, v52, v53
	v_add_f32_e32 v124, v124, v50
	v_add_f32_e32 v125, v125, v51
	v_cvt_pk_bf16_f32 v127, v54, v55
	v_add_f32_e32 v124, v124, v52
	v_add_f32_e32 v125, v125, v53
	v_cvt_pk_bf16_f32 v156, v56, v57
	v_add_f32_e32 v124, v124, v54
	v_add_f32_e32 v125, v125, v55
	v_cvt_pk_bf16_f32 v157, v58, v59
	v_add_f32_e32 v124, v124, v56
	v_add_f32_e32 v125, v125, v57
	v_cvt_pk_bf16_f32 v158, v60, v61
	v_add_f32_e32 v124, v124, v58
	v_add_f32_e32 v125, v125, v59
	v_cvt_pk_bf16_f32 v159, v62, v63
	v_add_f32_e32 v124, v124, v60
	v_add_f32_e32 v125, v125, v61
	v_add_f32_e32 v161, v124, v62
	v_add_f32_e32 v162, v125, v63
	v_cvt_pk_bf16_f32 v124, v48, v49
	v_cvt_pk_bf16_f32 v125, v50, v51
	s_waitcnt lgkmcnt(0)
	s_nop 0
	v_mfma_f32_32x32x16_bf16 v[0:15], v[140:143], v[124:127], v[0:15]
	v_exp_f32_e32 v64, v64
	v_exp_f32_e32 v65, v65
	v_exp_f32_e32 v66, v66
	v_exp_f32_e32 v67, v67
	v_exp_f32_e32 v68, v68
	v_exp_f32_e32 v69, v69
	v_exp_f32_e32 v70, v70
	v_mfma_f32_32x32x16_bf16 v[16:31], v[148:151], v[124:127], v[16:31]
	v_exp_f32_e32 v71, v71
	v_exp_f32_e32 v72, v72
	v_exp_f32_e32 v73, v73
	v_exp_f32_e32 v74, v74
	v_exp_f32_e32 v75, v75
	v_exp_f32_e32 v76, v76
	v_exp_f32_e32 v77, v77
	v_mfma_f32_32x32x16_bf16 v[0:15], v[144:147], v[156:159], v[0:15]
	ds_read_b64_tr_b16 v[124:125], v160 offset:6144
	ds_read_b64_tr_b16 v[126:127], v160 offset:6656
	ds_read_b64_tr_b16 v[140:141], v160 offset:10240
	ds_read_b64_tr_b16 v[142:143], v160 offset:10752
	ds_read_b64_tr_b16 v[144:145], v160 offset:7168
	ds_read_b64_tr_b16 v[146:147], v160 offset:7680
	ds_read_b64_tr_b16 v[148:149], v160 offset:11264
	ds_read_b64_tr_b16 v[150:151], v160 offset:11776
	v_exp_f32_e32 v78, v78
	v_exp_f32_e32 v79, v79
	s_nop 1
	v_mfma_f32_32x32x16_bf16 v[16:31], v[152:155], v[156:159], v[16:31]
	v_add_f32_e32 v152, v161, v64
	v_add_f32_e32 v153, v162, v65
	v_cvt_pk_bf16_f32 v154, v68, v69
	v_add_f32_e32 v152, v152, v66
	v_add_f32_e32 v153, v153, v67
	v_cvt_pk_bf16_f32 v155, v70, v71
	v_add_f32_e32 v152, v152, v68
	v_add_f32_e32 v153, v153, v69
	v_cvt_pk_bf16_f32 v156, v72, v73
	v_add_f32_e32 v152, v152, v70
	v_add_f32_e32 v153, v153, v71
	v_cvt_pk_bf16_f32 v157, v74, v75
	v_add_f32_e32 v152, v152, v72
	v_add_f32_e32 v153, v153, v73
	v_cvt_pk_bf16_f32 v158, v76, v77
	v_add_f32_e32 v152, v152, v74
	v_add_f32_e32 v153, v153, v75
	v_cvt_pk_bf16_f32 v159, v78, v79
	v_add_f32_e32 v152, v152, v76
	v_add_f32_e32 v153, v153, v77
	v_add_f32_e32 v160, v152, v78
	v_add_f32_e32 v161, v153, v79
	v_cvt_pk_bf16_f32 v152, v64, v65
	s_nop 0
	v_cvt_pk_bf16_f32 v153, v66, v67
	v_add_f32_e32 v160, v160, v161
	s_waitcnt lgkmcnt(0)
	v_mfma_f32_32x32x16_bf16 v[0:15], v[124:127], v[152:155], v[0:15]
	s_waitcnt vmcnt(2) lgkmcnt(0)
	s_barrier
	v_add_f32_e32 v139, v139, v160
	s_cmp_ge_u32 s4, s40
	v_mfma_f32_32x32x16_bf16 v[16:31], v[140:143], v[152:155], v[16:31]
	v_mfma_f32_32x32x16_bf16 v[0:15], v[144:147], v[156:159], v[0:15]
	v_mfma_f32_32x32x16_bf16 v[16:31], v[148:151], v[156:159], v[16:31]
	v_mfma_f32_32x32x16_bf16 v[80:95], v[120:123], v[116:119], v[80:95]
	s_cbranch_scc1 .LBB0_743
	s_min_u32 s4, s17, s40
	s_mul_hi_u32 s5, s4, 0x55555556
	s_mul_i32 s5, s5, 3
	s_sub_i32 s5, s4, s5
	s_mul_i32 s6, s5, 0x3000
	s_mul_i32 s4, s4, 0x50000
	s_mov_b32 s5, s81
	v_lshl_add_u64 v[48:49], v[128:129], 0, s[4:5]
	v_lshl_add_u64 v[48:49], v[48:49], 0, s[90:91]
	s_add_i32 m0, s93, s6
	s_add_i32 s4, s41, s95
	global_load_lds_dwordx4 v[48:49], off
	v_lshl_add_u64 v[48:49], v[130:131], 0, s[80:81]
	v_lshl_add_u64 v[48:49], v[48:49], 0, s[0:1]
	s_add_i32 m0, s4, 0x1000
	s_cmp_le_u32 s19, s39
	global_load_lds_dwordx4 v[48:49], off
	s_cbranch_scc1 .LBB0_751
	v_subrev_u32_e32 v48, 64, v137
	v_cmp_lt_i32_e32 vcc, -1, v48
	s_nop 1
	v_cndmask_b32_e32 v96, v249, v96, vcc
	v_cmp_lt_i32_e32 vcc, 31, v48
	s_nop 1
	v_cndmask_b32_e32 v80, v249, v80, vcc
	v_cmp_lt_i32_e32 vcc, 0, v48
	s_nop 1
	v_cndmask_b32_e32 v97, v249, v97, vcc
	v_cmp_lt_i32_e32 vcc, 32, v48
	s_nop 1
	v_cndmask_b32_e32 v81, v249, v81, vcc
	v_cmp_lt_i32_e32 vcc, 1, v48
	s_nop 1
	v_cndmask_b32_e32 v98, v249, v98, vcc
	v_cmp_lt_i32_e32 vcc, 33, v48
	s_nop 1
	v_cndmask_b32_e32 v82, v249, v82, vcc
	v_cmp_lt_i32_e32 vcc, 2, v48
	s_nop 1
	v_cndmask_b32_e32 v99, v249, v99, vcc
	v_cmp_lt_i32_e32 vcc, 34, v48
	s_nop 1
	v_cndmask_b32_e32 v83, v249, v83, vcc
	v_cmp_lt_i32_e32 vcc, 7, v48
	s_nop 1
	v_cndmask_b32_e32 v100, v249, v100, vcc
	v_cmp_lt_i32_e32 vcc, 39, v48
	s_nop 1
	v_cndmask_b32_e32 v84, v249, v84, vcc
	v_cmp_lt_i32_e32 vcc, 8, v48
	s_nop 1
	v_cndmask_b32_e32 v101, v249, v101, vcc
	v_cmp_lt_i32_e32 vcc, 40, v48
	s_nop 1
	v_cndmask_b32_e32 v85, v249, v85, vcc
	v_cmp_lt_i32_e32 vcc, 9, v48
	s_nop 1
	v_cndmask_b32_e32 v102, v249, v102, vcc
	v_cmp_lt_i32_e32 vcc, 41, v48
	s_nop 1
	v_cndmask_b32_e32 v86, v249, v86, vcc
	v_cmp_lt_i32_e32 vcc, 10, v48
	s_nop 1
	v_cndmask_b32_e32 v103, v249, v103, vcc
	v_cmp_lt_i32_e32 vcc, 42, v48
	s_nop 1
	v_cndmask_b32_e32 v87, v249, v87, vcc
	v_cmp_lt_i32_e32 vcc, 15, v48
	s_nop 1
	v_cndmask_b32_e32 v104, v249, v104, vcc
	v_cmp_lt_i32_e32 vcc, 47, v48
	s_nop 1
	v_cndmask_b32_e32 v88, v249, v88, vcc
	v_cmp_lt_i32_e32 vcc, 16, v48
	s_nop 1
	v_cndmask_b32_e32 v105, v249, v105, vcc
	v_cmp_lt_i32_e32 vcc, 48, v48
	s_nop 1
	v_cndmask_b32_e32 v89, v249, v89, vcc
	v_cmp_lt_i32_e32 vcc, 17, v48
	s_nop 1
	v_cndmask_b32_e32 v106, v249, v106, vcc
	v_cmp_lt_i32_e32 vcc, 49, v48
	s_nop 1
	v_cndmask_b32_e32 v90, v249, v90, vcc
	v_cmp_lt_i32_e32 vcc, 18, v48
	s_nop 1
	v_cndmask_b32_e32 v107, v249, v107, vcc
	v_cmp_lt_i32_e32 vcc, 50, v48
	s_nop 1
	v_cndmask_b32_e32 v91, v249, v91, vcc
	v_cmp_lt_i32_e32 vcc, 23, v48
	s_nop 1
	v_cndmask_b32_e32 v108, v249, v108, vcc
	v_cmp_lt_i32_e32 vcc, 55, v48
	s_nop 1
	v_cndmask_b32_e32 v92, v249, v92, vcc
	v_cmp_lt_i32_e32 vcc, 24, v48
	s_nop 1
	v_cndmask_b32_e32 v109, v249, v109, vcc
	v_cmp_lt_i32_e32 vcc, 56, v48
	s_nop 1
	v_cndmask_b32_e32 v93, v249, v93, vcc
	v_cmp_lt_i32_e32 vcc, 25, v48
	s_nop 1
	v_cndmask_b32_e32 v110, v249, v110, vcc
	v_cmp_lt_i32_e32 vcc, 57, v48
	s_nop 1
	v_cndmask_b32_e32 v94, v249, v94, vcc
	v_cmp_lt_i32_e32 vcc, 26, v48
	s_nop 1
	v_cndmask_b32_e32 v111, v249, v111, vcc
	v_cmp_lt_i32_e32 vcc, 58, v48
	s_nop 1
	v_cndmask_b32_e32 v95, v249, v95, vcc
.LBB0_751:
	v_add3_u32 v48, s21, v133, v134
	ds_read_b128 v[68:71], v48
	ds_read_b128 v[124:127], v48 offset:512
	ds_read_b128 v[64:67], v48 offset:2048
	ds_read_b128 v[120:123], v48 offset:2560
	s_nop 0
	v_max3_f32 v48, v96, v80, v97
	v_max3_f32 v49, v81, v98, v82
	v_max3_f32 v48, v48, v99, v83
	v_max3_f32 v49, v49, v100, v84
	v_max3_f32 v48, v48, v101, v85
	v_max3_f32 v49, v49, v102, v86
	v_max3_f32 v48, v48, v103, v87
	v_max3_f32 v49, v49, v104, v88
	v_max3_f32 v48, v48, v105, v89
	v_max3_f32 v49, v49, v106, v90
	v_max3_f32 v48, v48, v107, v91
	v_max3_f32 v49, v49, v108, v92
	v_max3_f32 v48, v48, v109, v93
	v_max3_f32 v49, v49, v110, v94
	v_max3_f32 v48, v48, v111, v95
	v_max_f32_e32 v49, v49, v49
	v_max_f32_e32 v48, v48, v48
	v_max_f32_e32 v48, v48, v49
	v_mov_b32_e32 v49, v48
	s_nop 1
	v_permlane32_swap_b32_e32 v48, v49
	v_max_f32_e32 v49, v49, v49
	v_max_f32_e32 v48, v48, v48
	v_max_f32_e32 v48, v48, v49
	v_cmp_lt_f32_e32 vcc, s97, v48
	v_cmp_lg_f32_e64 s[4:5], s96, v48
	s_nop 0
	v_cndmask_b32_e64 v49, 0, 1, vcc
	v_cndmask_b32_e64 v50, 0, 1, s[4:5]
	v_cndmask_b32_e64 v49, v50, v49, s[2:3]
	v_and_b32_e32 v49, 1, v49
	v_cmp_eq_u32_e64 s[6:7], 1, v49
	v_cmp_ne_u32_e32 vcc, 0, v49
	s_cbranch_vccz .LBB0_742
	v_cndmask_b32_e64 v32, 0, v48, s[6:7]
	v_exp_f32_e64 v34, -v32
	s_or_b64 s[4:5], s[2:3], s[4:5]
	v_add_f32_e32 v138, v138, v32
	v_pk_add_f32 v[96:97], v[96:97], v[32:33] op_sel_hi:[1,0] neg_lo:[0,1] neg_hi:[0,1]
	v_pk_add_f32 v[80:81], v[80:81], v[32:33] op_sel_hi:[1,0] neg_lo:[0,1] neg_hi:[0,1]
	v_pk_add_f32 v[98:99], v[98:99], v[32:33] op_sel_hi:[1,0] neg_lo:[0,1] neg_hi:[0,1]
	v_pk_add_f32 v[82:83], v[82:83], v[32:33] op_sel_hi:[1,0] neg_lo:[0,1] neg_hi:[0,1]
	v_pk_add_f32 v[100:101], v[100:101], v[32:33] op_sel_hi:[1,0] neg_lo:[0,1] neg_hi:[0,1]
	v_pk_add_f32 v[84:85], v[84:85], v[32:33] op_sel_hi:[1,0] neg_lo:[0,1] neg_hi:[0,1]
	v_pk_add_f32 v[102:103], v[102:103], v[32:33] op_sel_hi:[1,0] neg_lo:[0,1] neg_hi:[0,1]
	v_pk_add_f32 v[86:87], v[86:87], v[32:33] op_sel_hi:[1,0] neg_lo:[0,1] neg_hi:[0,1]
	v_pk_add_f32 v[104:105], v[104:105], v[32:33] op_sel_hi:[1,0] neg_lo:[0,1] neg_hi:[0,1]
	v_pk_add_f32 v[88:89], v[88:89], v[32:33] op_sel_hi:[1,0] neg_lo:[0,1] neg_hi:[0,1]
	v_pk_add_f32 v[106:107], v[106:107], v[32:33] op_sel_hi:[1,0] neg_lo:[0,1] neg_hi:[0,1]
	v_pk_add_f32 v[90:91], v[90:91], v[32:33] op_sel_hi:[1,0] neg_lo:[0,1] neg_hi:[0,1]
	v_pk_add_f32 v[108:109], v[108:109], v[32:33] op_sel_hi:[1,0] neg_lo:[0,1] neg_hi:[0,1]
	v_pk_add_f32 v[92:93], v[92:93], v[32:33] op_sel_hi:[1,0] neg_lo:[0,1] neg_hi:[0,1]
	v_pk_add_f32 v[110:111], v[110:111], v[32:33] op_sel_hi:[1,0] neg_lo:[0,1] neg_hi:[0,1]
	v_pk_add_f32 v[94:95], v[94:95], v[32:33] op_sel_hi:[1,0] neg_lo:[0,1] neg_hi:[0,1]
	v_xor_b32_e32 v32, 0x80000000, v138
	s_andn2_b64 s[2:3], s[2:3], exec
	s_and_b64 s[4:5], s[4:5], exec
	v_mul_f32_e32 v139, v139, v34
	v_pk_mul_f32 v[30:31], v[30:31], v[34:35] op_sel_hi:[1,0]
	v_pk_mul_f32 v[28:29], v[28:29], v[34:35] op_sel_hi:[1,0]
	v_pk_mul_f32 v[26:27], v[26:27], v[34:35] op_sel_hi:[1,0]
	v_pk_mul_f32 v[24:25], v[24:25], v[34:35] op_sel_hi:[1,0]
	v_pk_mul_f32 v[22:23], v[22:23], v[34:35] op_sel_hi:[1,0]
	v_pk_mul_f32 v[20:21], v[20:21], v[34:35] op_sel_hi:[1,0]
	v_pk_mul_f32 v[18:19], v[18:19], v[34:35] op_sel_hi:[1,0]
	v_pk_mul_f32 v[16:17], v[16:17], v[34:35] op_sel_hi:[1,0]
	v_pk_mul_f32 v[14:15], v[14:15], v[34:35] op_sel_hi:[1,0]
	v_pk_mul_f32 v[12:13], v[12:13], v[34:35] op_sel_hi:[1,0]
	v_pk_mul_f32 v[10:11], v[10:11], v[34:35] op_sel_hi:[1,0]
	v_pk_mul_f32 v[8:9], v[8:9], v[34:35] op_sel_hi:[1,0]
	v_pk_mul_f32 v[6:7], v[6:7], v[34:35] op_sel_hi:[1,0]
	v_pk_mul_f32 v[4:5], v[4:5], v[34:35] op_sel_hi:[1,0]
	v_pk_mul_f32 v[2:3], v[2:3], v[34:35] op_sel_hi:[1,0]
	v_pk_mul_f32 v[0:1], v[0:1], v[34:35] op_sel_hi:[1,0]
	v_mov_b32_e32 v33, v32
	v_mov_b32_e32 v34, v32
	v_mov_b32_e32 v35, v32
	v_mov_b32_e32 v36, v32
	v_mov_b32_e32 v37, v32
	v_mov_b32_e32 v38, v32
	v_mov_b32_e32 v39, v32
	v_mov_b32_e32 v40, v32
	v_mov_b32_e32 v41, v32
	v_mov_b32_e32 v42, v32
	v_mov_b32_e32 v43, v32
	v_mov_b32_e32 v44, v32
	v_mov_b32_e32 v45, v32
	v_mov_b32_e32 v46, v32
	v_mov_b32_e32 v47, v32
	s_or_b64 s[2:3], s[2:3], s[4:5]
	s_branch .LBB0_742
